# saddr-form global_load_lds in 5 big GEMM K-loops (drops 16 v_lshl_add_u64 per iteration)
# speedup vs baseline: 1.0089x; 1.0089x over previous
.LBB0_272:
	ds_read_b128 v[154:157], v148
	ds_read_b128 v[158:161], v148 offset:1024
	ds_read_b128 v[164:167], v148 offset:2048
	ds_read_b128 v[168:171], v148 offset:3072
	ds_read_b128 v[172:175], v149
	ds_read_b128 v[176:179], v149 offset:1024
	ds_read_b128 v[180:183], v149 offset:2048
	ds_read_b128 v[184:187], v149 offset:3072
	s_add_u32 s24, s22, 0xfff00080
	s_addc_u32 s25, s23, -1
	s_cmp_eq_u32 s56, 60
	s_cselect_b32 s27, s51, s25
	s_cselect_b32 s26, s52, s24
	s_cselect_b32 s25, s7, s55
	s_cselect_b32 s24, s53, s54
	s_mov_b32 m0, s40
	ds_read_b128 v[188:191], v150
	ds_read_b128 v[192:195], v150 offset:1024
	ds_read_b128 v[196:199], v150 offset:2048
	ds_read_b128 v[200:203], v150 offset:3072
	ds_read_b128 v[204:207], v150 offset:4096
	ds_read_b128 v[208:211], v150 offset:5120
	ds_read_b128 v[212:215], v150 offset:6144
	ds_read_b128 v[216:219], v150 offset:7168
	global_load_lds_dwordx4 v142, s[22:23]
	s_mov_b32 m0, s41
	s_nop 0
	global_load_lds_dwordx4 v144, s[22:23]
	s_waitcnt vmcnt(8)
	s_waitcnt lgkmcnt(0)
	s_barrier
	s_setprio 1
	s_waitcnt lgkmcnt(0)
	v_mfma_f32_16x16x32_bf16 v[126:129], v[154:157], v[188:191], v[126:129]
	v_mfma_f32_16x16x32_bf16 v[122:125], v[164:167], v[188:191], v[122:125]
	v_mfma_f32_16x16x32_bf16 v[118:121], v[154:157], v[196:199], v[118:121]
	v_mfma_f32_16x16x32_bf16 v[114:117], v[164:167], v[196:199], v[114:117]
	v_mfma_f32_16x16x32_bf16 v[102:105], v[154:157], v[204:207], v[102:105]
	v_mfma_f32_16x16x32_bf16 v[98:101], v[164:167], v[204:207], v[98:101]
	v_mfma_f32_16x16x32_bf16 v[86:89], v[154:157], v[212:215], v[86:89]
	v_mfma_f32_16x16x32_bf16 v[82:85], v[164:167], v[212:215], v[82:85]
	v_mfma_f32_16x16x32_bf16 v[126:129], v[158:161], v[192:195], v[126:129]
	v_mfma_f32_16x16x32_bf16 v[122:125], v[168:171], v[192:195], v[122:125]
	v_mfma_f32_16x16x32_bf16 v[118:121], v[158:161], v[200:203], v[118:121]
	v_mfma_f32_16x16x32_bf16 v[114:117], v[168:171], v[200:203], v[114:117]
	v_mfma_f32_16x16x32_bf16 v[102:105], v[158:161], v[208:211], v[102:105]
	v_mfma_f32_16x16x32_bf16 v[98:101], v[168:171], v[208:211], v[98:101]
	v_mfma_f32_16x16x32_bf16 v[86:89], v[158:161], v[216:219], v[86:89]
	v_mfma_f32_16x16x32_bf16 v[82:85], v[168:171], v[216:219], v[82:85]
	s_setprio 0
	s_setprio 1
	v_mfma_f32_16x16x32_bf16 v[110:113], v[172:175], v[188:191], v[110:113]
	v_mfma_f32_16x16x32_bf16 v[106:109], v[180:183], v[188:191], v[106:109]
	v_mfma_f32_16x16x32_bf16 v[94:97], v[172:175], v[196:199], v[94:97]
	v_mfma_f32_16x16x32_bf16 v[90:93], v[180:183], v[196:199], v[90:93]
	v_mfma_f32_16x16x32_bf16 v[78:81], v[172:175], v[204:207], v[78:81]
	v_mfma_f32_16x16x32_bf16 v[74:77], v[180:183], v[204:207], v[74:77]
	v_mfma_f32_16x16x32_bf16 v[70:73], v[172:175], v[212:215], v[70:73]
	v_mfma_f32_16x16x32_bf16 v[66:69], v[180:183], v[212:215], v[66:69]
	v_mfma_f32_16x16x32_bf16 v[110:113], v[176:179], v[192:195], v[110:113]
	v_mfma_f32_16x16x32_bf16 v[106:109], v[184:187], v[192:195], v[106:109]
	v_mfma_f32_16x16x32_bf16 v[94:97], v[176:179], v[200:203], v[94:97]
	v_mfma_f32_16x16x32_bf16 v[90:93], v[184:187], v[200:203], v[90:93]
	v_mfma_f32_16x16x32_bf16 v[78:81], v[176:179], v[208:211], v[78:81]
	v_mfma_f32_16x16x32_bf16 v[74:77], v[184:187], v[208:211], v[74:77]
	v_mfma_f32_16x16x32_bf16 v[70:73], v[176:179], v[216:219], v[70:73]
	v_mfma_f32_16x16x32_bf16 v[66:69], v[184:187], v[216:219], v[66:69]
	s_setprio 0
	s_barrier
	s_mov_b32 m0, s42
	s_add_u32 s58, s24, 0x100000
	ds_read_b128 v[188:191], v150 offset:16384
	ds_read_b128 v[192:195], v150 offset:17408
	ds_read_b128 v[196:199], v150 offset:18432
	ds_read_b128 v[200:203], v150 offset:19456
	ds_read_b128 v[204:207], v150 offset:20480
	ds_read_b128 v[208:211], v150 offset:21504
	ds_read_b128 v[212:215], v150 offset:22528
	ds_read_b128 v[216:219], v150 offset:23552
	global_load_lds_dwordx4 v132, s[24:25]
	s_mov_b32 m0, s43
	s_addc_u32 s59, s25, 0
	global_load_lds_dwordx4 v136, s[24:25]
	s_mov_b32 m0, s44
	s_nop 0
	global_load_lds_dwordx4 v132, s[58:59]
	s_mov_b32 m0, s45
	s_nop 0
	global_load_lds_dwordx4 v136, s[58:59]
	s_mov_b32 m0, s30
	s_nop 0
	global_load_lds_dwordx4 v130, s[26:27]
	s_mov_b32 m0, s31
	s_nop 0
	global_load_lds_dwordx4 v134, s[26:27]
	s_waitcnt vmcnt(8)
	s_waitcnt lgkmcnt(0)
	s_barrier
	s_setprio 1
	s_waitcnt lgkmcnt(0)
	v_mfma_f32_16x16x32_bf16 v[62:65], v[154:157], v[188:191], v[62:65]
	v_mfma_f32_16x16x32_bf16 v[58:61], v[164:167], v[188:191], v[58:61]
	v_mfma_f32_16x16x32_bf16 v[54:57], v[154:157], v[196:199], v[54:57]
	v_mfma_f32_16x16x32_bf16 v[50:53], v[164:167], v[196:199], v[50:53]
	v_mfma_f32_16x16x32_bf16 v[38:41], v[154:157], v[204:207], v[38:41]
	v_mfma_f32_16x16x32_bf16 v[34:37], v[164:167], v[204:207], v[34:37]
	v_mfma_f32_16x16x32_bf16 v[22:25], v[154:157], v[212:215], v[22:25]
	v_mfma_f32_16x16x32_bf16 v[18:21], v[164:167], v[212:215], v[18:21]
	v_mfma_f32_16x16x32_bf16 v[62:65], v[158:161], v[192:195], v[62:65]
	v_mfma_f32_16x16x32_bf16 v[58:61], v[168:171], v[192:195], v[58:61]
	v_mfma_f32_16x16x32_bf16 v[54:57], v[158:161], v[200:203], v[54:57]
	v_mfma_f32_16x16x32_bf16 v[50:53], v[168:171], v[200:203], v[50:53]
	v_mfma_f32_16x16x32_bf16 v[38:41], v[158:161], v[208:211], v[38:41]
	v_mfma_f32_16x16x32_bf16 v[34:37], v[168:171], v[208:211], v[34:37]
	v_mfma_f32_16x16x32_bf16 v[22:25], v[158:161], v[216:219], v[22:25]
	v_mfma_f32_16x16x32_bf16 v[18:21], v[168:171], v[216:219], v[18:21]
	s_setprio 0
	s_setprio 1
	v_mfma_f32_16x16x32_bf16 v[46:49], v[172:175], v[188:191], v[46:49]
	v_mfma_f32_16x16x32_bf16 v[42:45], v[180:183], v[188:191], v[42:45]
	v_mfma_f32_16x16x32_bf16 v[30:33], v[172:175], v[196:199], v[30:33]
	v_mfma_f32_16x16x32_bf16 v[26:29], v[180:183], v[196:199], v[26:29]
	v_mfma_f32_16x16x32_bf16 v[14:17], v[172:175], v[204:207], v[14:17]
	v_mfma_f32_16x16x32_bf16 v[10:13], v[180:183], v[204:207], v[10:13]
	v_mfma_f32_16x16x32_bf16 v[6:9], v[172:175], v[212:215], v[6:9]
	v_mfma_f32_16x16x32_bf16 v[2:5], v[180:183], v[212:215], v[2:5]
	v_mfma_f32_16x16x32_bf16 v[46:49], v[176:179], v[192:195], v[46:49]
	v_mfma_f32_16x16x32_bf16 v[42:45], v[184:187], v[192:195], v[42:45]
	v_mfma_f32_16x16x32_bf16 v[30:33], v[176:179], v[200:203], v[30:33]
	v_mfma_f32_16x16x32_bf16 v[26:29], v[184:187], v[200:203], v[26:29]
	v_mfma_f32_16x16x32_bf16 v[14:17], v[176:179], v[208:211], v[14:17]
	v_mfma_f32_16x16x32_bf16 v[10:13], v[184:187], v[208:211], v[10:13]
	v_mfma_f32_16x16x32_bf16 v[6:9], v[176:179], v[216:219], v[6:9]
	v_mfma_f32_16x16x32_bf16 v[2:5], v[184:187], v[216:219], v[2:5]
	s_setprio 0
	s_barrier
	ds_read_b128 v[154:157], v151
	ds_read_b128 v[158:161], v151 offset:1024
	ds_read_b128 v[164:167], v151 offset:2048
	ds_read_b128 v[168:171], v151 offset:3072
	ds_read_b128 v[172:175], v152
	ds_read_b128 v[176:179], v152 offset:1024
	ds_read_b128 v[180:183], v152 offset:2048
	ds_read_b128 v[184:187], v152 offset:3072
	s_add_u32 s26, s26, 0x100000
	s_addc_u32 s27, s27, 0
	s_mov_b32 m0, s33
	ds_read_b128 v[188:191], v150 offset:32768
	ds_read_b128 v[192:195], v150 offset:33792
	ds_read_b128 v[196:199], v150 offset:34816
	ds_read_b128 v[200:203], v150 offset:35840
	ds_read_b128 v[204:207], v150 offset:36864
	ds_read_b128 v[208:211], v150 offset:37888
	ds_read_b128 v[212:215], v150 offset:38912
	ds_read_b128 v[216:219], v150 offset:39936
	global_load_lds_dwordx4 v130, s[26:27]
	s_mov_b32 m0, s34
	s_nop 0
	global_load_lds_dwordx4 v134, s[26:27]
	s_waitcnt vmcnt(8)
	s_waitcnt lgkmcnt(0)
	s_barrier
	s_setprio 1
	s_waitcnt lgkmcnt(0)
	v_mfma_f32_16x16x32_bf16 v[126:129], v[154:157], v[188:191], v[126:129]
	v_mfma_f32_16x16x32_bf16 v[122:125], v[164:167], v[188:191], v[122:125]
	v_mfma_f32_16x16x32_bf16 v[118:121], v[154:157], v[196:199], v[118:121]
	v_mfma_f32_16x16x32_bf16 v[114:117], v[164:167], v[196:199], v[114:117]
	v_mfma_f32_16x16x32_bf16 v[102:105], v[154:157], v[204:207], v[102:105]
	v_mfma_f32_16x16x32_bf16 v[98:101], v[164:167], v[204:207], v[98:101]
	v_mfma_f32_16x16x32_bf16 v[86:89], v[154:157], v[212:215], v[86:89]
	v_mfma_f32_16x16x32_bf16 v[82:85], v[164:167], v[212:215], v[82:85]
	v_mfma_f32_16x16x32_bf16 v[126:129], v[158:161], v[192:195], v[126:129]
	v_mfma_f32_16x16x32_bf16 v[122:125], v[168:171], v[192:195], v[122:125]
	v_mfma_f32_16x16x32_bf16 v[118:121], v[158:161], v[200:203], v[118:121]
	v_mfma_f32_16x16x32_bf16 v[114:117], v[168:171], v[200:203], v[114:117]
	v_mfma_f32_16x16x32_bf16 v[102:105], v[158:161], v[208:211], v[102:105]
	v_mfma_f32_16x16x32_bf16 v[98:101], v[168:171], v[208:211], v[98:101]
	v_mfma_f32_16x16x32_bf16 v[86:89], v[158:161], v[216:219], v[86:89]
	v_mfma_f32_16x16x32_bf16 v[82:85], v[168:171], v[216:219], v[82:85]
	s_setprio 0
	s_setprio 1
	v_mfma_f32_16x16x32_bf16 v[110:113], v[172:175], v[188:191], v[110:113]
	v_mfma_f32_16x16x32_bf16 v[106:109], v[180:183], v[188:191], v[106:109]
	v_mfma_f32_16x16x32_bf16 v[94:97], v[172:175], v[196:199], v[94:97]
	v_mfma_f32_16x16x32_bf16 v[90:93], v[180:183], v[196:199], v[90:93]
	v_mfma_f32_16x16x32_bf16 v[78:81], v[172:175], v[204:207], v[78:81]
	v_mfma_f32_16x16x32_bf16 v[74:77], v[180:183], v[204:207], v[74:77]
	v_mfma_f32_16x16x32_bf16 v[70:73], v[172:175], v[212:215], v[70:73]
	v_mfma_f32_16x16x32_bf16 v[66:69], v[180:183], v[212:215], v[66:69]
	v_mfma_f32_16x16x32_bf16 v[110:113], v[176:179], v[192:195], v[110:113]
	v_mfma_f32_16x16x32_bf16 v[106:109], v[184:187], v[192:195], v[106:109]
	v_mfma_f32_16x16x32_bf16 v[94:97], v[176:179], v[200:203], v[94:97]
	v_mfma_f32_16x16x32_bf16 v[90:93], v[184:187], v[200:203], v[90:93]
	v_mfma_f32_16x16x32_bf16 v[78:81], v[176:179], v[208:211], v[78:81]
	v_mfma_f32_16x16x32_bf16 v[74:77], v[184:187], v[208:211], v[74:77]
	v_mfma_f32_16x16x32_bf16 v[70:73], v[176:179], v[216:219], v[70:73]
	v_mfma_f32_16x16x32_bf16 v[66:69], v[184:187], v[216:219], v[66:69]
	s_setprio 0
	s_barrier
	s_mov_b32 m0, s47
	s_add_u32 s24, s24, 0x80
	s_addc_u32 s25, s25, 0
	ds_read_b128 v[188:191], v150 offset:49152
	ds_read_b128 v[192:195], v150 offset:50176
	ds_read_b128 v[196:199], v150 offset:51200
	ds_read_b128 v[200:203], v150 offset:52224
	ds_read_b128 v[204:207], v150 offset:53248
	ds_read_b128 v[208:211], v150 offset:54272
	ds_read_b128 v[212:215], v150 offset:55296
	ds_read_b128 v[216:219], v150 offset:56320
	global_load_lds_dwordx4 v132, s[24:25]
	s_mov_b32 m0, s48
	s_add_u32 s58, s26, 0xfff00080
	s_addc_u32 s59, s27, -1
	global_load_lds_dwordx4 v136, s[24:25]
	s_add_i32 s26, s46, s29
	s_mov_b32 m0, s26
	s_add_u32 s24, s24, 0x100000
	s_addc_u32 s25, s25, 0
	global_load_lds_dwordx4 v132, s[24:25]
	s_add_i32 m0, s26, 0x2000
	s_nop 0
	global_load_lds_dwordx4 v136, s[24:25]
	s_mov_b32 m0, s36
	s_nop 0
	global_load_lds_dwordx4 v130, s[58:59]
	s_mov_b32 m0, s37
	s_nop 0
	global_load_lds_dwordx4 v134, s[58:59]
	s_waitcnt vmcnt(8)
	s_waitcnt lgkmcnt(0)
	s_barrier
	s_setprio 1
	s_waitcnt lgkmcnt(0)
	v_mfma_f32_16x16x32_bf16 v[62:65], v[154:157], v[188:191], v[62:65]
	v_mfma_f32_16x16x32_bf16 v[58:61], v[164:167], v[188:191], v[58:61]
	v_mfma_f32_16x16x32_bf16 v[54:57], v[154:157], v[196:199], v[54:57]
	v_mfma_f32_16x16x32_bf16 v[50:53], v[164:167], v[196:199], v[50:53]
	v_mfma_f32_16x16x32_bf16 v[38:41], v[154:157], v[204:207], v[38:41]
	v_mfma_f32_16x16x32_bf16 v[34:37], v[164:167], v[204:207], v[34:37]
	v_mfma_f32_16x16x32_bf16 v[22:25], v[154:157], v[212:215], v[22:25]
	v_mfma_f32_16x16x32_bf16 v[18:21], v[164:167], v[212:215], v[18:21]
	v_mfma_f32_16x16x32_bf16 v[62:65], v[158:161], v[192:195], v[62:65]
	v_mfma_f32_16x16x32_bf16 v[58:61], v[168:171], v[192:195], v[58:61]
	v_mfma_f32_16x16x32_bf16 v[54:57], v[158:161], v[200:203], v[54:57]
	v_mfma_f32_16x16x32_bf16 v[50:53], v[168:171], v[200:203], v[50:53]
	v_mfma_f32_16x16x32_bf16 v[38:41], v[158:161], v[208:211], v[38:41]
	v_mfma_f32_16x16x32_bf16 v[34:37], v[168:171], v[208:211], v[34:37]
	v_mfma_f32_16x16x32_bf16 v[22:25], v[158:161], v[216:219], v[22:25]
	v_mfma_f32_16x16x32_bf16 v[18:21], v[168:171], v[216:219], v[18:21]
	s_setprio 0
	s_setprio 1
	v_mfma_f32_16x16x32_bf16 v[46:49], v[172:175], v[188:191], v[46:49]
	v_mfma_f32_16x16x32_bf16 v[42:45], v[180:183], v[188:191], v[42:45]
	v_mfma_f32_16x16x32_bf16 v[30:33], v[172:175], v[196:199], v[30:33]
	v_mfma_f32_16x16x32_bf16 v[26:29], v[180:183], v[196:199], v[26:29]
	v_mfma_f32_16x16x32_bf16 v[14:17], v[172:175], v[204:207], v[14:17]
	v_mfma_f32_16x16x32_bf16 v[10:13], v[180:183], v[204:207], v[10:13]
	v_mfma_f32_16x16x32_bf16 v[6:9], v[172:175], v[212:215], v[6:9]
	v_mfma_f32_16x16x32_bf16 v[2:5], v[180:183], v[212:215], v[2:5]
	v_mfma_f32_16x16x32_bf16 v[46:49], v[176:179], v[192:195], v[46:49]
	v_mfma_f32_16x16x32_bf16 v[42:45], v[184:187], v[192:195], v[42:45]
	v_mfma_f32_16x16x32_bf16 v[30:33], v[176:179], v[200:203], v[30:33]
	v_mfma_f32_16x16x32_bf16 v[26:29], v[184:187], v[200:203], v[26:29]
	v_mfma_f32_16x16x32_bf16 v[14:17], v[176:179], v[208:211], v[14:17]
	v_mfma_f32_16x16x32_bf16 v[10:13], v[184:187], v[208:211], v[10:13]
	v_mfma_f32_16x16x32_bf16 v[6:9], v[176:179], v[216:219], v[6:9]
	v_mfma_f32_16x16x32_bf16 v[2:5], v[184:187], v[216:219], v[2:5]
	s_setprio 0
	s_barrier
	s_add_i32 s56, s56, 2
	s_add_u32 s22, s22, 0x100
	s_addc_u32 s23, s23, 0
	s_add_u32 s54, s54, 0x100
	s_addc_u32 s55, s55, 0
	s_cmp_gt_u32 s56, 61
	s_cbranch_scc0 .LBB0_272
	s_and_b64 vcc, exec, s[16:17]
	s_cbranch_vccz .LBB0_277
	s_barrier
	v_lshl_add_u32 v138, s50, 8, v1
	s_cmp_gt_i32 s49, 63
	s_mov_b64 s[22:23], -1
	s_cbranch_scc1 .LBB0_278

.LBB0_1172:
	ds_read_b128 v[142:145], v148
	ds_read_b128 v[154:157], v148 offset:1024
	ds_read_b128 v[158:161], v148 offset:2048
	ds_read_b128 v[168:171], v148 offset:3072
	ds_read_b128 v[176:179], v149
	ds_read_b128 v[180:183], v149 offset:1024
	ds_read_b128 v[184:187], v149 offset:2048
	ds_read_b128 v[188:191], v149 offset:3072
	s_add_u32 s22, s20, 0xfff00080
	s_addc_u32 s23, s21, -1
	s_cmp_eq_u32 s61, 60
	s_cselect_b32 s25, s54, s23
	s_cselect_b32 s24, s55, s22
	s_cselect_b32 s23, s7, s60
	s_cselect_b32 s22, s56, s57
	s_mov_b32 m0, s42
	ds_read_b128 v[192:195], v150
	ds_read_b128 v[202:205], v150 offset:1024
	ds_read_b128 v[206:209], v150 offset:2048
	ds_read_b128 v[210:213], v150 offset:3072
	ds_read_b128 v[214:217], v150 offset:4096
	ds_read_b128 v[218:221], v150 offset:5120
	ds_read_b128 v[222:225], v150 offset:6144
	ds_read_b128 v[226:229], v150 offset:7168
	global_load_lds_dwordx4 v138, s[20:21]
	s_mov_b32 m0, s43
	s_nop 0
	global_load_lds_dwordx4 v140, s[20:21]
	s_waitcnt vmcnt(8)
	s_waitcnt lgkmcnt(0)
	s_barrier
	s_setprio 1
	s_waitcnt lgkmcnt(0)
	v_mfma_f32_16x16x32_bf16 v[126:129], v[142:145], v[192:195], v[126:129]
	v_mfma_f32_16x16x32_bf16 v[118:121], v[158:161], v[192:195], v[118:121]
	v_mfma_f32_16x16x32_bf16 v[110:113], v[142:145], v[206:209], v[110:113]
	v_mfma_f32_16x16x32_bf16 v[102:105], v[158:161], v[206:209], v[102:105]
	v_mfma_f32_16x16x32_bf16 v[94:97], v[142:145], v[214:217], v[94:97]
	v_mfma_f32_16x16x32_bf16 v[86:89], v[158:161], v[214:217], v[86:89]
	v_mfma_f32_16x16x32_bf16 v[78:81], v[142:145], v[222:225], v[78:81]
	v_mfma_f32_16x16x32_bf16 v[70:73], v[158:161], v[222:225], v[70:73]
	v_mfma_f32_16x16x32_bf16 v[126:129], v[154:157], v[202:205], v[126:129]
	v_mfma_f32_16x16x32_bf16 v[118:121], v[168:171], v[202:205], v[118:121]
	v_mfma_f32_16x16x32_bf16 v[110:113], v[154:157], v[210:213], v[110:113]
	v_mfma_f32_16x16x32_bf16 v[102:105], v[168:171], v[210:213], v[102:105]
	v_mfma_f32_16x16x32_bf16 v[94:97], v[154:157], v[218:221], v[94:97]
	v_mfma_f32_16x16x32_bf16 v[86:89], v[168:171], v[218:221], v[86:89]
	v_mfma_f32_16x16x32_bf16 v[78:81], v[154:157], v[226:229], v[78:81]
	v_mfma_f32_16x16x32_bf16 v[70:73], v[168:171], v[226:229], v[70:73]
	s_setprio 0
	s_setprio 1
	v_mfma_f32_16x16x32_bf16 v[122:125], v[176:179], v[192:195], v[122:125]
	v_mfma_f32_16x16x32_bf16 v[114:117], v[184:187], v[192:195], v[114:117]
	v_mfma_f32_16x16x32_bf16 v[106:109], v[176:179], v[206:209], v[106:109]
	v_mfma_f32_16x16x32_bf16 v[98:101], v[184:187], v[206:209], v[98:101]
	v_mfma_f32_16x16x32_bf16 v[90:93], v[176:179], v[214:217], v[90:93]
	v_mfma_f32_16x16x32_bf16 v[82:85], v[184:187], v[214:217], v[82:85]
	v_mfma_f32_16x16x32_bf16 v[74:77], v[176:179], v[222:225], v[74:77]
	v_mfma_f32_16x16x32_bf16 v[66:69], v[184:187], v[222:225], v[66:69]
	v_mfma_f32_16x16x32_bf16 v[122:125], v[180:183], v[202:205], v[122:125]
	v_mfma_f32_16x16x32_bf16 v[114:117], v[188:191], v[202:205], v[114:117]
	v_mfma_f32_16x16x32_bf16 v[106:109], v[180:183], v[210:213], v[106:109]
	v_mfma_f32_16x16x32_bf16 v[98:101], v[188:191], v[210:213], v[98:101]
	v_mfma_f32_16x16x32_bf16 v[90:93], v[180:183], v[218:221], v[90:93]
	v_mfma_f32_16x16x32_bf16 v[82:85], v[188:191], v[218:221], v[82:85]
	v_mfma_f32_16x16x32_bf16 v[74:77], v[180:183], v[226:229], v[74:77]
	v_mfma_f32_16x16x32_bf16 v[66:69], v[188:191], v[226:229], v[66:69]
	s_setprio 0
	s_barrier
	s_mov_b32 m0, s44
	s_add_u32 s62, s22, 0x100000
	ds_read_b128 v[192:195], v150 offset:16384
	ds_read_b128 v[202:205], v150 offset:17408
	ds_read_b128 v[206:209], v150 offset:18432
	ds_read_b128 v[210:213], v150 offset:19456
	ds_read_b128 v[214:217], v150 offset:20480
	ds_read_b128 v[218:221], v150 offset:21504
	ds_read_b128 v[222:225], v150 offset:22528
	ds_read_b128 v[226:229], v150 offset:23552
	global_load_lds_dwordx4 v132, s[22:23]
	s_mov_b32 m0, s45
	s_addc_u32 s63, s23, 0
	global_load_lds_dwordx4 v136, s[22:23]
	s_mov_b32 m0, s46
	s_nop 0
	global_load_lds_dwordx4 v132, s[62:63]
	s_mov_b32 m0, s47
	s_nop 0
	global_load_lds_dwordx4 v136, s[62:63]
	s_mov_b32 m0, s31
	s_nop 0
	global_load_lds_dwordx4 v130, s[24:25]
	s_mov_b32 m0, s33
	s_nop 0
	global_load_lds_dwordx4 v134, s[24:25]
	s_waitcnt vmcnt(8)
	s_waitcnt lgkmcnt(0)
	s_barrier
	s_setprio 1
	s_waitcnt lgkmcnt(0)
	v_mfma_f32_16x16x32_bf16 v[62:65], v[142:145], v[192:195], v[62:65]
	v_mfma_f32_16x16x32_bf16 v[54:57], v[158:161], v[192:195], v[54:57]
	v_mfma_f32_16x16x32_bf16 v[46:49], v[142:145], v[206:209], v[46:49]
	v_mfma_f32_16x16x32_bf16 v[38:41], v[158:161], v[206:209], v[38:41]
	v_mfma_f32_16x16x32_bf16 v[30:33], v[142:145], v[214:217], v[30:33]
	v_mfma_f32_16x16x32_bf16 v[22:25], v[158:161], v[214:217], v[22:25]
	v_mfma_f32_16x16x32_bf16 v[14:17], v[142:145], v[222:225], v[14:17]
	v_mfma_f32_16x16x32_bf16 v[6:9], v[158:161], v[222:225], v[6:9]
	v_mfma_f32_16x16x32_bf16 v[62:65], v[154:157], v[202:205], v[62:65]
	v_mfma_f32_16x16x32_bf16 v[54:57], v[168:171], v[202:205], v[54:57]
	v_mfma_f32_16x16x32_bf16 v[46:49], v[154:157], v[210:213], v[46:49]
	v_mfma_f32_16x16x32_bf16 v[38:41], v[168:171], v[210:213], v[38:41]
	v_mfma_f32_16x16x32_bf16 v[30:33], v[154:157], v[218:221], v[30:33]
	v_mfma_f32_16x16x32_bf16 v[22:25], v[168:171], v[218:221], v[22:25]
	v_mfma_f32_16x16x32_bf16 v[14:17], v[154:157], v[226:229], v[14:17]
	v_mfma_f32_16x16x32_bf16 v[6:9], v[168:171], v[226:229], v[6:9]
	s_setprio 0
	s_setprio 1
	v_mfma_f32_16x16x32_bf16 v[58:61], v[176:179], v[192:195], v[58:61]
	v_mfma_f32_16x16x32_bf16 v[50:53], v[184:187], v[192:195], v[50:53]
	v_mfma_f32_16x16x32_bf16 v[42:45], v[176:179], v[206:209], v[42:45]
	v_mfma_f32_16x16x32_bf16 v[34:37], v[184:187], v[206:209], v[34:37]
	v_mfma_f32_16x16x32_bf16 v[26:29], v[176:179], v[214:217], v[26:29]
	v_mfma_f32_16x16x32_bf16 v[18:21], v[184:187], v[214:217], v[18:21]
	v_mfma_f32_16x16x32_bf16 v[10:13], v[176:179], v[222:225], v[10:13]
	v_mfma_f32_16x16x32_bf16 v[2:5], v[184:187], v[222:225], v[2:5]
	v_mfma_f32_16x16x32_bf16 v[58:61], v[180:183], v[202:205], v[58:61]
	v_mfma_f32_16x16x32_bf16 v[50:53], v[188:191], v[202:205], v[50:53]
	v_mfma_f32_16x16x32_bf16 v[42:45], v[180:183], v[210:213], v[42:45]
	v_mfma_f32_16x16x32_bf16 v[34:37], v[188:191], v[210:213], v[34:37]
	v_mfma_f32_16x16x32_bf16 v[26:29], v[180:183], v[218:221], v[26:29]
	v_mfma_f32_16x16x32_bf16 v[18:21], v[188:191], v[218:221], v[18:21]
	v_mfma_f32_16x16x32_bf16 v[10:13], v[180:183], v[226:229], v[10:13]
	v_mfma_f32_16x16x32_bf16 v[2:5], v[188:191], v[226:229], v[2:5]
	s_setprio 0
	s_barrier
	ds_read_b128 v[142:145], v151
	ds_read_b128 v[154:157], v151 offset:1024
	ds_read_b128 v[158:161], v151 offset:2048
	ds_read_b128 v[168:171], v151 offset:3072
	ds_read_b128 v[176:179], v152
	ds_read_b128 v[180:183], v152 offset:1024
	ds_read_b128 v[184:187], v152 offset:2048
	ds_read_b128 v[188:191], v152 offset:3072
	s_add_u32 s24, s24, 0x100000
	s_addc_u32 s25, s25, 0
	s_mov_b32 m0, s34
	ds_read_b128 v[192:195], v150 offset:32768
	ds_read_b128 v[202:205], v150 offset:33792
	ds_read_b128 v[206:209], v150 offset:34816
	ds_read_b128 v[210:213], v150 offset:35840
	ds_read_b128 v[214:217], v150 offset:36864
	ds_read_b128 v[218:221], v150 offset:37888
	ds_read_b128 v[222:225], v150 offset:38912
	ds_read_b128 v[226:229], v150 offset:39936
	global_load_lds_dwordx4 v130, s[24:25]
	s_mov_b32 m0, s35
	s_nop 0
	global_load_lds_dwordx4 v134, s[24:25]
	s_waitcnt vmcnt(8)
	s_waitcnt lgkmcnt(0)
	s_barrier
	s_setprio 1
	s_waitcnt lgkmcnt(0)
	v_mfma_f32_16x16x32_bf16 v[126:129], v[142:145], v[192:195], v[126:129]
	v_mfma_f32_16x16x32_bf16 v[118:121], v[158:161], v[192:195], v[118:121]
	v_mfma_f32_16x16x32_bf16 v[110:113], v[142:145], v[206:209], v[110:113]
	v_mfma_f32_16x16x32_bf16 v[102:105], v[158:161], v[206:209], v[102:105]
	v_mfma_f32_16x16x32_bf16 v[94:97], v[142:145], v[214:217], v[94:97]
	v_mfma_f32_16x16x32_bf16 v[86:89], v[158:161], v[214:217], v[86:89]
	v_mfma_f32_16x16x32_bf16 v[78:81], v[142:145], v[222:225], v[78:81]
	v_mfma_f32_16x16x32_bf16 v[70:73], v[158:161], v[222:225], v[70:73]
	v_mfma_f32_16x16x32_bf16 v[126:129], v[154:157], v[202:205], v[126:129]
	v_mfma_f32_16x16x32_bf16 v[118:121], v[168:171], v[202:205], v[118:121]
	v_mfma_f32_16x16x32_bf16 v[110:113], v[154:157], v[210:213], v[110:113]
	v_mfma_f32_16x16x32_bf16 v[102:105], v[168:171], v[210:213], v[102:105]
	v_mfma_f32_16x16x32_bf16 v[94:97], v[154:157], v[218:221], v[94:97]
	v_mfma_f32_16x16x32_bf16 v[86:89], v[168:171], v[218:221], v[86:89]
	v_mfma_f32_16x16x32_bf16 v[78:81], v[154:157], v[226:229], v[78:81]
	v_mfma_f32_16x16x32_bf16 v[70:73], v[168:171], v[226:229], v[70:73]
	s_setprio 0
	s_setprio 1
	v_mfma_f32_16x16x32_bf16 v[122:125], v[176:179], v[192:195], v[122:125]
	v_mfma_f32_16x16x32_bf16 v[114:117], v[184:187], v[192:195], v[114:117]
	v_mfma_f32_16x16x32_bf16 v[106:109], v[176:179], v[206:209], v[106:109]
	v_mfma_f32_16x16x32_bf16 v[98:101], v[184:187], v[206:209], v[98:101]
	v_mfma_f32_16x16x32_bf16 v[90:93], v[176:179], v[214:217], v[90:93]
	v_mfma_f32_16x16x32_bf16 v[82:85], v[184:187], v[214:217], v[82:85]
	v_mfma_f32_16x16x32_bf16 v[74:77], v[176:179], v[222:225], v[74:77]
	v_mfma_f32_16x16x32_bf16 v[66:69], v[184:187], v[222:225], v[66:69]
	v_mfma_f32_16x16x32_bf16 v[122:125], v[180:183], v[202:205], v[122:125]
	v_mfma_f32_16x16x32_bf16 v[114:117], v[188:191], v[202:205], v[114:117]
	v_mfma_f32_16x16x32_bf16 v[106:109], v[180:183], v[210:213], v[106:109]
	v_mfma_f32_16x16x32_bf16 v[98:101], v[188:191], v[210:213], v[98:101]
	v_mfma_f32_16x16x32_bf16 v[90:93], v[180:183], v[218:221], v[90:93]
	v_mfma_f32_16x16x32_bf16 v[82:85], v[188:191], v[218:221], v[82:85]
	v_mfma_f32_16x16x32_bf16 v[74:77], v[180:183], v[226:229], v[74:77]
	v_mfma_f32_16x16x32_bf16 v[66:69], v[188:191], v[226:229], v[66:69]
	s_setprio 0
	s_barrier
	s_mov_b32 m0, s48
	s_add_u32 s22, s22, 0x80
	s_addc_u32 s23, s23, 0
	ds_read_b128 v[192:195], v150 offset:49152
	ds_read_b128 v[202:205], v150 offset:50176
	ds_read_b128 v[206:209], v150 offset:51200
	ds_read_b128 v[210:213], v150 offset:52224
	ds_read_b128 v[214:217], v150 offset:53248
	ds_read_b128 v[218:221], v150 offset:54272
	ds_read_b128 v[222:225], v150 offset:55296
	ds_read_b128 v[226:229], v150 offset:56320
	global_load_lds_dwordx4 v132, s[22:23]
	s_mov_b32 m0, s49
	s_add_u32 s62, s24, 0xfff00080
	s_addc_u32 s63, s25, -1
	global_load_lds_dwordx4 v136, s[22:23]
	s_mov_b32 m0, s50
	s_add_u32 s22, s22, 0x100000
	s_addc_u32 s23, s23, 0
	global_load_lds_dwordx4 v132, s[22:23]
	s_mov_b32 m0, s51
	s_nop 0
	global_load_lds_dwordx4 v136, s[22:23]
	s_mov_b32 m0, s37
	s_nop 0
	global_load_lds_dwordx4 v130, s[62:63]
	s_mov_b32 m0, s38
	s_nop 0
	global_load_lds_dwordx4 v134, s[62:63]
	s_waitcnt vmcnt(8)
	s_waitcnt lgkmcnt(0)
	s_barrier
	s_setprio 1
	s_waitcnt lgkmcnt(0)
	v_mfma_f32_16x16x32_bf16 v[62:65], v[142:145], v[192:195], v[62:65]
	v_mfma_f32_16x16x32_bf16 v[54:57], v[158:161], v[192:195], v[54:57]
	v_mfma_f32_16x16x32_bf16 v[46:49], v[142:145], v[206:209], v[46:49]
	v_mfma_f32_16x16x32_bf16 v[38:41], v[158:161], v[206:209], v[38:41]
	v_mfma_f32_16x16x32_bf16 v[30:33], v[142:145], v[214:217], v[30:33]
	v_mfma_f32_16x16x32_bf16 v[22:25], v[158:161], v[214:217], v[22:25]
	v_mfma_f32_16x16x32_bf16 v[14:17], v[142:145], v[222:225], v[14:17]
	v_mfma_f32_16x16x32_bf16 v[6:9], v[158:161], v[222:225], v[6:9]
	v_mfma_f32_16x16x32_bf16 v[62:65], v[154:157], v[202:205], v[62:65]
	v_mfma_f32_16x16x32_bf16 v[54:57], v[168:171], v[202:205], v[54:57]
	v_mfma_f32_16x16x32_bf16 v[46:49], v[154:157], v[210:213], v[46:49]
	v_mfma_f32_16x16x32_bf16 v[38:41], v[168:171], v[210:213], v[38:41]
	v_mfma_f32_16x16x32_bf16 v[30:33], v[154:157], v[218:221], v[30:33]
	v_mfma_f32_16x16x32_bf16 v[22:25], v[168:171], v[218:221], v[22:25]
	v_mfma_f32_16x16x32_bf16 v[14:17], v[154:157], v[226:229], v[14:17]
	v_mfma_f32_16x16x32_bf16 v[6:9], v[168:171], v[226:229], v[6:9]
	s_setprio 0
	s_setprio 1
	v_mfma_f32_16x16x32_bf16 v[58:61], v[176:179], v[192:195], v[58:61]
	v_mfma_f32_16x16x32_bf16 v[50:53], v[184:187], v[192:195], v[50:53]
	v_mfma_f32_16x16x32_bf16 v[42:45], v[176:179], v[206:209], v[42:45]
	v_mfma_f32_16x16x32_bf16 v[34:37], v[184:187], v[206:209], v[34:37]
	v_mfma_f32_16x16x32_bf16 v[26:29], v[176:179], v[214:217], v[26:29]
	v_mfma_f32_16x16x32_bf16 v[18:21], v[184:187], v[214:217], v[18:21]
	v_mfma_f32_16x16x32_bf16 v[10:13], v[176:179], v[222:225], v[10:13]
	v_mfma_f32_16x16x32_bf16 v[2:5], v[184:187], v[222:225], v[2:5]
	v_mfma_f32_16x16x32_bf16 v[58:61], v[180:183], v[202:205], v[58:61]
	v_mfma_f32_16x16x32_bf16 v[50:53], v[188:191], v[202:205], v[50:53]
	v_mfma_f32_16x16x32_bf16 v[42:45], v[180:183], v[210:213], v[42:45]
	v_mfma_f32_16x16x32_bf16 v[34:37], v[188:191], v[210:213], v[34:37]
	v_mfma_f32_16x16x32_bf16 v[26:29], v[180:183], v[218:221], v[26:29]
	v_mfma_f32_16x16x32_bf16 v[18:21], v[188:191], v[218:221], v[18:21]
	v_mfma_f32_16x16x32_bf16 v[10:13], v[180:183], v[226:229], v[10:13]
	v_mfma_f32_16x16x32_bf16 v[2:5], v[188:191], v[226:229], v[2:5]
	s_setprio 0
	s_barrier
	s_add_i32 s61, s61, 2
	s_add_u32 s20, s20, 0x100
	s_addc_u32 s21, s21, 0
	s_add_u32 s57, s57, 0x100
	s_addc_u32 s60, s60, 0
	s_cmp_gt_u32 s61, 61
	s_cbranch_scc0 .LBB0_1172
	s_and_b64 vcc, exec, s[16:17]
	s_cbranch_vccz .LBB0_1175
	s_barrier

.LBB0_1418:
	ds_read_b128 v[142:145], v156
	ds_read_b128 v[168:171], v156 offset:1024
	ds_read_b128 v[176:179], v156 offset:2048
	ds_read_b128 v[180:183], v156 offset:3072
	ds_read_b128 v[184:187], v157
	ds_read_b128 v[188:191], v157 offset:1024
	ds_read_b128 v[192:195], v157 offset:2048
	ds_read_b128 v[204:207], v157 offset:3072
	s_add_u32 s24, s22, 0xffd50080
	s_addc_u32 s25, s23, -1
	s_cmpk_eq_i32 s55, 0xa8
	s_cselect_b32 s27, s19, s25
	s_cselect_b32 s26, s18, s24
	s_cselect_b32 s25, s17, s54
	s_cselect_b32 s24, s16, s53
	s_mov_b32 m0, s42
	ds_read_b128 v[208:211], v158
	ds_read_b128 v[212:215], v158 offset:1024
	ds_read_b128 v[216:219], v158 offset:2048
	ds_read_b128 v[220:223], v158 offset:3072
	ds_read_b128 v[224:227], v158 offset:4096
	ds_read_b128 v[228:231], v158 offset:5120
	ds_read_b128 v[232:235], v158 offset:6144
	ds_read_b128 v[236:239], v158 offset:7168
	global_load_lds_dwordx4 v138, s[22:23]
	s_mov_b32 m0, s43
	s_nop 0
	global_load_lds_dwordx4 v140, s[22:23]
	s_waitcnt vmcnt(8)
	s_waitcnt lgkmcnt(0)
	s_barrier
	s_setprio 1
	s_waitcnt lgkmcnt(0)
	v_mfma_f32_16x16x32_bf16 v[126:129], v[142:145], v[208:211], v[126:129]
	v_mfma_f32_16x16x32_bf16 v[122:125], v[176:179], v[208:211], v[122:125]
	v_mfma_f32_16x16x32_bf16 v[110:113], v[142:145], v[216:219], v[110:113]
	v_mfma_f32_16x16x32_bf16 v[106:109], v[176:179], v[216:219], v[106:109]
	v_mfma_f32_16x16x32_bf16 v[94:97], v[142:145], v[224:227], v[94:97]
	v_mfma_f32_16x16x32_bf16 v[90:93], v[176:179], v[224:227], v[90:93]
	v_mfma_f32_16x16x32_bf16 v[78:81], v[142:145], v[232:235], v[78:81]
	v_mfma_f32_16x16x32_bf16 v[74:77], v[176:179], v[232:235], v[74:77]
	v_mfma_f32_16x16x32_bf16 v[126:129], v[168:171], v[212:215], v[126:129]
	v_mfma_f32_16x16x32_bf16 v[122:125], v[180:183], v[212:215], v[122:125]
	v_mfma_f32_16x16x32_bf16 v[110:113], v[168:171], v[220:223], v[110:113]
	v_mfma_f32_16x16x32_bf16 v[106:109], v[180:183], v[220:223], v[106:109]
	v_mfma_f32_16x16x32_bf16 v[94:97], v[168:171], v[228:231], v[94:97]
	v_mfma_f32_16x16x32_bf16 v[90:93], v[180:183], v[228:231], v[90:93]
	v_mfma_f32_16x16x32_bf16 v[78:81], v[168:171], v[236:239], v[78:81]
	v_mfma_f32_16x16x32_bf16 v[74:77], v[180:183], v[236:239], v[74:77]
	s_setprio 0
	s_setprio 1
	v_mfma_f32_16x16x32_bf16 v[118:121], v[184:187], v[208:211], v[118:121]
	v_mfma_f32_16x16x32_bf16 v[114:117], v[192:195], v[208:211], v[114:117]
	v_mfma_f32_16x16x32_bf16 v[102:105], v[184:187], v[216:219], v[102:105]
	v_mfma_f32_16x16x32_bf16 v[98:101], v[192:195], v[216:219], v[98:101]
	v_mfma_f32_16x16x32_bf16 v[86:89], v[184:187], v[224:227], v[86:89]
	v_mfma_f32_16x16x32_bf16 v[82:85], v[192:195], v[224:227], v[82:85]
	v_mfma_f32_16x16x32_bf16 v[70:73], v[184:187], v[232:235], v[70:73]
	v_mfma_f32_16x16x32_bf16 v[66:69], v[192:195], v[232:235], v[66:69]
	v_mfma_f32_16x16x32_bf16 v[118:121], v[188:191], v[212:215], v[118:121]
	v_mfma_f32_16x16x32_bf16 v[114:117], v[204:207], v[212:215], v[114:117]
	v_mfma_f32_16x16x32_bf16 v[102:105], v[188:191], v[220:223], v[102:105]
	v_mfma_f32_16x16x32_bf16 v[98:101], v[204:207], v[220:223], v[98:101]
	v_mfma_f32_16x16x32_bf16 v[86:89], v[188:191], v[228:231], v[86:89]
	v_mfma_f32_16x16x32_bf16 v[82:85], v[204:207], v[228:231], v[82:85]
	v_mfma_f32_16x16x32_bf16 v[70:73], v[188:191], v[236:239], v[70:73]
	v_mfma_f32_16x16x32_bf16 v[66:69], v[204:207], v[236:239], v[66:69]
	s_setprio 0
	s_barrier
	s_mov_b32 m0, s44
	s_add_u32 s56, s24, 0x2b0000
	ds_read_b128 v[208:211], v158 offset:16384
	ds_read_b128 v[212:215], v158 offset:17408
	ds_read_b128 v[216:219], v158 offset:18432
	ds_read_b128 v[220:223], v158 offset:19456
	ds_read_b128 v[224:227], v158 offset:20480
	ds_read_b128 v[228:231], v158 offset:21504
	ds_read_b128 v[232:235], v158 offset:22528
	ds_read_b128 v[236:239], v158 offset:23552
	global_load_lds_dwordx4 v132, s[24:25]
	s_mov_b32 m0, s45
	s_addc_u32 s57, s25, 0
	global_load_lds_dwordx4 v136, s[24:25]
	s_mov_b32 m0, s46
	s_nop 0
	global_load_lds_dwordx4 v132, s[56:57]
	s_mov_b32 m0, s47
	s_nop 0
	global_load_lds_dwordx4 v136, s[56:57]
	s_mov_b32 m0, s35
	s_nop 0
	global_load_lds_dwordx4 v130, s[26:27]
	s_mov_b32 m0, s36
	s_nop 0
	global_load_lds_dwordx4 v134, s[26:27]
	s_waitcnt vmcnt(8)
	s_waitcnt lgkmcnt(0)
	s_barrier
	s_setprio 1
	s_waitcnt lgkmcnt(0)
	v_mfma_f32_16x16x32_bf16 v[62:65], v[142:145], v[208:211], v[62:65]
	v_mfma_f32_16x16x32_bf16 v[58:61], v[176:179], v[208:211], v[58:61]
	v_mfma_f32_16x16x32_bf16 v[46:49], v[142:145], v[216:219], v[46:49]
	v_mfma_f32_16x16x32_bf16 v[42:45], v[176:179], v[216:219], v[42:45]
	v_mfma_f32_16x16x32_bf16 v[30:33], v[142:145], v[224:227], v[30:33]
	v_mfma_f32_16x16x32_bf16 v[26:29], v[176:179], v[224:227], v[26:29]
	v_mfma_f32_16x16x32_bf16 v[14:17], v[142:145], v[232:235], v[14:17]
	v_mfma_f32_16x16x32_bf16 v[10:13], v[176:179], v[232:235], v[10:13]
	v_mfma_f32_16x16x32_bf16 v[62:65], v[168:171], v[212:215], v[62:65]
	v_mfma_f32_16x16x32_bf16 v[58:61], v[180:183], v[212:215], v[58:61]
	v_mfma_f32_16x16x32_bf16 v[46:49], v[168:171], v[220:223], v[46:49]
	v_mfma_f32_16x16x32_bf16 v[42:45], v[180:183], v[220:223], v[42:45]
	v_mfma_f32_16x16x32_bf16 v[30:33], v[168:171], v[228:231], v[30:33]
	v_mfma_f32_16x16x32_bf16 v[26:29], v[180:183], v[228:231], v[26:29]
	v_mfma_f32_16x16x32_bf16 v[14:17], v[168:171], v[236:239], v[14:17]
	v_mfma_f32_16x16x32_bf16 v[10:13], v[180:183], v[236:239], v[10:13]
	s_setprio 0
	s_setprio 1
	v_mfma_f32_16x16x32_bf16 v[54:57], v[184:187], v[208:211], v[54:57]
	v_mfma_f32_16x16x32_bf16 v[50:53], v[192:195], v[208:211], v[50:53]
	v_mfma_f32_16x16x32_bf16 v[38:41], v[184:187], v[216:219], v[38:41]
	v_mfma_f32_16x16x32_bf16 v[34:37], v[192:195], v[216:219], v[34:37]
	v_mfma_f32_16x16x32_bf16 v[22:25], v[184:187], v[224:227], v[22:25]
	v_mfma_f32_16x16x32_bf16 v[18:21], v[192:195], v[224:227], v[18:21]
	v_mfma_f32_16x16x32_bf16 v[6:9], v[184:187], v[232:235], v[6:9]
	v_mfma_f32_16x16x32_bf16 v[2:5], v[192:195], v[232:235], v[2:5]
	v_mfma_f32_16x16x32_bf16 v[54:57], v[188:191], v[212:215], v[54:57]
	v_mfma_f32_16x16x32_bf16 v[50:53], v[204:207], v[212:215], v[50:53]
	v_mfma_f32_16x16x32_bf16 v[38:41], v[188:191], v[220:223], v[38:41]
	v_mfma_f32_16x16x32_bf16 v[34:37], v[204:207], v[220:223], v[34:37]
	v_mfma_f32_16x16x32_bf16 v[22:25], v[188:191], v[228:231], v[22:25]
	v_mfma_f32_16x16x32_bf16 v[18:21], v[204:207], v[228:231], v[18:21]
	v_mfma_f32_16x16x32_bf16 v[6:9], v[188:191], v[236:239], v[6:9]
	v_mfma_f32_16x16x32_bf16 v[2:5], v[204:207], v[236:239], v[2:5]
	s_setprio 0
	s_barrier
	ds_read_b128 v[142:145], v159
	ds_read_b128 v[168:171], v159 offset:1024
	ds_read_b128 v[176:179], v159 offset:2048
	ds_read_b128 v[180:183], v159 offset:3072
	ds_read_b128 v[184:187], v160
	ds_read_b128 v[188:191], v160 offset:1024
	ds_read_b128 v[192:195], v160 offset:2048
	ds_read_b128 v[204:207], v160 offset:3072
	s_add_u32 s26, s26, 0x2b0000
	s_addc_u32 s27, s27, 0
	s_mov_b32 m0, s37
	ds_read_b128 v[208:211], v158 offset:32768
	ds_read_b128 v[212:215], v158 offset:33792
	ds_read_b128 v[216:219], v158 offset:34816
	ds_read_b128 v[220:223], v158 offset:35840
	ds_read_b128 v[224:227], v158 offset:36864
	ds_read_b128 v[228:231], v158 offset:37888
	ds_read_b128 v[232:235], v158 offset:38912
	ds_read_b128 v[236:239], v158 offset:39936
	global_load_lds_dwordx4 v130, s[26:27]
	s_mov_b32 m0, s38
	s_nop 0
	global_load_lds_dwordx4 v134, s[26:27]
	s_waitcnt vmcnt(8)
	s_waitcnt lgkmcnt(0)
	s_barrier
	s_setprio 1
	s_waitcnt lgkmcnt(0)
	v_mfma_f32_16x16x32_bf16 v[126:129], v[142:145], v[208:211], v[126:129]
	v_mfma_f32_16x16x32_bf16 v[122:125], v[176:179], v[208:211], v[122:125]
	v_mfma_f32_16x16x32_bf16 v[110:113], v[142:145], v[216:219], v[110:113]
	v_mfma_f32_16x16x32_bf16 v[106:109], v[176:179], v[216:219], v[106:109]
	v_mfma_f32_16x16x32_bf16 v[94:97], v[142:145], v[224:227], v[94:97]
	v_mfma_f32_16x16x32_bf16 v[90:93], v[176:179], v[224:227], v[90:93]
	v_mfma_f32_16x16x32_bf16 v[78:81], v[142:145], v[232:235], v[78:81]
	v_mfma_f32_16x16x32_bf16 v[74:77], v[176:179], v[232:235], v[74:77]
	v_mfma_f32_16x16x32_bf16 v[126:129], v[168:171], v[212:215], v[126:129]
	v_mfma_f32_16x16x32_bf16 v[122:125], v[180:183], v[212:215], v[122:125]
	v_mfma_f32_16x16x32_bf16 v[110:113], v[168:171], v[220:223], v[110:113]
	v_mfma_f32_16x16x32_bf16 v[106:109], v[180:183], v[220:223], v[106:109]
	v_mfma_f32_16x16x32_bf16 v[94:97], v[168:171], v[228:231], v[94:97]
	v_mfma_f32_16x16x32_bf16 v[90:93], v[180:183], v[228:231], v[90:93]
	v_mfma_f32_16x16x32_bf16 v[78:81], v[168:171], v[236:239], v[78:81]
	v_mfma_f32_16x16x32_bf16 v[74:77], v[180:183], v[236:239], v[74:77]
	s_setprio 0
	s_setprio 1
	v_mfma_f32_16x16x32_bf16 v[118:121], v[184:187], v[208:211], v[118:121]
	v_mfma_f32_16x16x32_bf16 v[114:117], v[192:195], v[208:211], v[114:117]
	v_mfma_f32_16x16x32_bf16 v[102:105], v[184:187], v[216:219], v[102:105]
	v_mfma_f32_16x16x32_bf16 v[98:101], v[192:195], v[216:219], v[98:101]
	v_mfma_f32_16x16x32_bf16 v[86:89], v[184:187], v[224:227], v[86:89]
	v_mfma_f32_16x16x32_bf16 v[82:85], v[192:195], v[224:227], v[82:85]
	v_mfma_f32_16x16x32_bf16 v[70:73], v[184:187], v[232:235], v[70:73]
	v_mfma_f32_16x16x32_bf16 v[66:69], v[192:195], v[232:235], v[66:69]
	v_mfma_f32_16x16x32_bf16 v[118:121], v[188:191], v[212:215], v[118:121]
	v_mfma_f32_16x16x32_bf16 v[114:117], v[204:207], v[212:215], v[114:117]
	v_mfma_f32_16x16x32_bf16 v[102:105], v[188:191], v[220:223], v[102:105]
	v_mfma_f32_16x16x32_bf16 v[98:101], v[204:207], v[220:223], v[98:101]
	v_mfma_f32_16x16x32_bf16 v[86:89], v[188:191], v[228:231], v[86:89]
	v_mfma_f32_16x16x32_bf16 v[82:85], v[204:207], v[228:231], v[82:85]
	v_mfma_f32_16x16x32_bf16 v[70:73], v[188:191], v[236:239], v[70:73]
	v_mfma_f32_16x16x32_bf16 v[66:69], v[204:207], v[236:239], v[66:69]
	s_setprio 0
	s_barrier
	s_mov_b32 m0, s48
	s_add_u32 s24, s24, 0x80
	s_addc_u32 s25, s25, 0
	ds_read_b128 v[208:211], v158 offset:49152
	ds_read_b128 v[212:215], v158 offset:50176
	ds_read_b128 v[216:219], v158 offset:51200
	ds_read_b128 v[220:223], v158 offset:52224
	ds_read_b128 v[224:227], v158 offset:53248
	ds_read_b128 v[228:231], v158 offset:54272
	ds_read_b128 v[232:235], v158 offset:55296
	ds_read_b128 v[236:239], v158 offset:56320
	global_load_lds_dwordx4 v132, s[24:25]
	s_mov_b32 m0, s49
	s_add_u32 s56, s26, 0xffd50080
	s_addc_u32 s57, s27, -1
	global_load_lds_dwordx4 v136, s[24:25]
	s_mov_b32 m0, s50
	s_add_u32 s24, s24, 0x2b0000
	s_addc_u32 s25, s25, 0
	global_load_lds_dwordx4 v132, s[24:25]
	s_add_i32 m0, s50, 0x2000
	s_nop 0
	global_load_lds_dwordx4 v136, s[24:25]
	s_mov_b32 m0, s40
	s_nop 0
	global_load_lds_dwordx4 v130, s[56:57]
	s_mov_b32 m0, s41
	s_nop 0
	global_load_lds_dwordx4 v134, s[56:57]
	s_waitcnt vmcnt(8)
	s_waitcnt lgkmcnt(0)
	s_barrier
	s_setprio 1
	s_waitcnt lgkmcnt(0)
	v_mfma_f32_16x16x32_bf16 v[62:65], v[142:145], v[208:211], v[62:65]
	v_mfma_f32_16x16x32_bf16 v[58:61], v[176:179], v[208:211], v[58:61]
	v_mfma_f32_16x16x32_bf16 v[46:49], v[142:145], v[216:219], v[46:49]
	v_mfma_f32_16x16x32_bf16 v[42:45], v[176:179], v[216:219], v[42:45]
	v_mfma_f32_16x16x32_bf16 v[30:33], v[142:145], v[224:227], v[30:33]
	v_mfma_f32_16x16x32_bf16 v[26:29], v[176:179], v[224:227], v[26:29]
	v_mfma_f32_16x16x32_bf16 v[14:17], v[142:145], v[232:235], v[14:17]
	v_mfma_f32_16x16x32_bf16 v[10:13], v[176:179], v[232:235], v[10:13]
	v_mfma_f32_16x16x32_bf16 v[62:65], v[168:171], v[212:215], v[62:65]
	v_mfma_f32_16x16x32_bf16 v[58:61], v[180:183], v[212:215], v[58:61]
	v_mfma_f32_16x16x32_bf16 v[46:49], v[168:171], v[220:223], v[46:49]
	v_mfma_f32_16x16x32_bf16 v[42:45], v[180:183], v[220:223], v[42:45]
	v_mfma_f32_16x16x32_bf16 v[30:33], v[168:171], v[228:231], v[30:33]
	v_mfma_f32_16x16x32_bf16 v[26:29], v[180:183], v[228:231], v[26:29]
	v_mfma_f32_16x16x32_bf16 v[14:17], v[168:171], v[236:239], v[14:17]
	v_mfma_f32_16x16x32_bf16 v[10:13], v[180:183], v[236:239], v[10:13]
	s_setprio 0
	s_setprio 1
	v_mfma_f32_16x16x32_bf16 v[54:57], v[184:187], v[208:211], v[54:57]
	v_mfma_f32_16x16x32_bf16 v[50:53], v[192:195], v[208:211], v[50:53]
	v_mfma_f32_16x16x32_bf16 v[38:41], v[184:187], v[216:219], v[38:41]
	v_mfma_f32_16x16x32_bf16 v[34:37], v[192:195], v[216:219], v[34:37]
	v_mfma_f32_16x16x32_bf16 v[22:25], v[184:187], v[224:227], v[22:25]
	v_mfma_f32_16x16x32_bf16 v[18:21], v[192:195], v[224:227], v[18:21]
	v_mfma_f32_16x16x32_bf16 v[6:9], v[184:187], v[232:235], v[6:9]
	v_mfma_f32_16x16x32_bf16 v[2:5], v[192:195], v[232:235], v[2:5]
	v_mfma_f32_16x16x32_bf16 v[54:57], v[188:191], v[212:215], v[54:57]
	v_mfma_f32_16x16x32_bf16 v[50:53], v[204:207], v[212:215], v[50:53]
	v_mfma_f32_16x16x32_bf16 v[38:41], v[188:191], v[220:223], v[38:41]
	v_mfma_f32_16x16x32_bf16 v[34:37], v[204:207], v[220:223], v[34:37]
	v_mfma_f32_16x16x32_bf16 v[22:25], v[188:191], v[228:231], v[22:25]
	v_mfma_f32_16x16x32_bf16 v[18:21], v[204:207], v[228:231], v[18:21]
	v_mfma_f32_16x16x32_bf16 v[6:9], v[188:191], v[236:239], v[6:9]
	v_mfma_f32_16x16x32_bf16 v[2:5], v[204:207], v[236:239], v[2:5]
	s_setprio 0
	s_barrier
	s_add_i32 s55, s55, 2
	s_add_u32 s22, s22, 0x100
	s_addc_u32 s23, s23, 0
	s_add_u32 s53, s53, 0x100
	s_addc_u32 s54, s54, 0
	s_cmpk_gt_u32 s55, 0xa9
	s_cbranch_scc0 .LBB0_1418
	s_and_b64 vcc, exec, s[14:15]
	s_cbranch_vccz .LBB0_1421
	s_barrier

.LBB0_2373:
	ds_read_b128 v[142:145], v148
	ds_read_b128 v[154:157], v148 offset:1024
	ds_read_b128 v[158:161], v148 offset:2048
	ds_read_b128 v[168:171], v148 offset:3072
	ds_read_b128 v[176:179], v149
	ds_read_b128 v[180:183], v149 offset:1024
	ds_read_b128 v[184:187], v149 offset:2048
	ds_read_b128 v[188:191], v149 offset:3072
	s_add_u32 s22, s20, 0xfff00080
	s_addc_u32 s23, s21, -1
	s_cmp_eq_u32 s57, 60
	s_cselect_b32 s25, s52, s23
	s_cselect_b32 s24, s53, s22
	s_cselect_b32 s23, s7, s56
	s_cselect_b32 s22, s54, s55
	s_mov_b32 m0, s40
	ds_read_b128 v[192:195], v150
	ds_read_b128 v[204:207], v150 offset:1024
	ds_read_b128 v[208:211], v150 offset:2048
	ds_read_b128 v[212:215], v150 offset:3072
	ds_read_b128 v[216:219], v150 offset:4096
	ds_read_b128 v[220:223], v150 offset:5120
	ds_read_b128 v[224:227], v150 offset:6144
	ds_read_b128 v[228:231], v150 offset:7168
	global_load_lds_dwordx4 v138, s[20:21]
	s_mov_b32 m0, s41
	s_nop 0
	global_load_lds_dwordx4 v140, s[20:21]
	s_waitcnt vmcnt(8)
	s_waitcnt lgkmcnt(0)
	s_barrier
	s_setprio 1
	s_waitcnt lgkmcnt(0)
	v_mfma_f32_16x16x32_bf16 v[126:129], v[142:145], v[192:195], v[126:129]
	v_mfma_f32_16x16x32_bf16 v[122:125], v[158:161], v[192:195], v[122:125]
	v_mfma_f32_16x16x32_bf16 v[110:113], v[142:145], v[208:211], v[110:113]
	v_mfma_f32_16x16x32_bf16 v[106:109], v[158:161], v[208:211], v[106:109]
	v_mfma_f32_16x16x32_bf16 v[94:97], v[142:145], v[216:219], v[94:97]
	v_mfma_f32_16x16x32_bf16 v[90:93], v[158:161], v[216:219], v[90:93]
	v_mfma_f32_16x16x32_bf16 v[78:81], v[142:145], v[224:227], v[78:81]
	v_mfma_f32_16x16x32_bf16 v[74:77], v[158:161], v[224:227], v[74:77]
	v_mfma_f32_16x16x32_bf16 v[126:129], v[154:157], v[204:207], v[126:129]
	v_mfma_f32_16x16x32_bf16 v[122:125], v[168:171], v[204:207], v[122:125]
	v_mfma_f32_16x16x32_bf16 v[110:113], v[154:157], v[212:215], v[110:113]
	v_mfma_f32_16x16x32_bf16 v[106:109], v[168:171], v[212:215], v[106:109]
	v_mfma_f32_16x16x32_bf16 v[94:97], v[154:157], v[220:223], v[94:97]
	v_mfma_f32_16x16x32_bf16 v[90:93], v[168:171], v[220:223], v[90:93]
	v_mfma_f32_16x16x32_bf16 v[78:81], v[154:157], v[228:231], v[78:81]
	v_mfma_f32_16x16x32_bf16 v[74:77], v[168:171], v[228:231], v[74:77]
	s_setprio 0
	s_setprio 1
	v_mfma_f32_16x16x32_bf16 v[118:121], v[176:179], v[192:195], v[118:121]
	v_mfma_f32_16x16x32_bf16 v[114:117], v[184:187], v[192:195], v[114:117]
	v_mfma_f32_16x16x32_bf16 v[102:105], v[176:179], v[208:211], v[102:105]
	v_mfma_f32_16x16x32_bf16 v[98:101], v[184:187], v[208:211], v[98:101]
	v_mfma_f32_16x16x32_bf16 v[86:89], v[176:179], v[216:219], v[86:89]
	v_mfma_f32_16x16x32_bf16 v[82:85], v[184:187], v[216:219], v[82:85]
	v_mfma_f32_16x16x32_bf16 v[70:73], v[176:179], v[224:227], v[70:73]
	v_mfma_f32_16x16x32_bf16 v[66:69], v[184:187], v[224:227], v[66:69]
	v_mfma_f32_16x16x32_bf16 v[118:121], v[180:183], v[204:207], v[118:121]
	v_mfma_f32_16x16x32_bf16 v[114:117], v[188:191], v[204:207], v[114:117]
	v_mfma_f32_16x16x32_bf16 v[102:105], v[180:183], v[212:215], v[102:105]
	v_mfma_f32_16x16x32_bf16 v[98:101], v[188:191], v[212:215], v[98:101]
	v_mfma_f32_16x16x32_bf16 v[86:89], v[180:183], v[220:223], v[86:89]
	v_mfma_f32_16x16x32_bf16 v[82:85], v[188:191], v[220:223], v[82:85]
	v_mfma_f32_16x16x32_bf16 v[70:73], v[180:183], v[228:231], v[70:73]
	v_mfma_f32_16x16x32_bf16 v[66:69], v[188:191], v[228:231], v[66:69]
	s_setprio 0
	s_barrier
	s_mov_b32 m0, s42
	s_add_u32 s60, s22, 0x100000
	ds_read_b128 v[192:195], v150 offset:16384
	ds_read_b128 v[204:207], v150 offset:17408
	ds_read_b128 v[208:211], v150 offset:18432
	ds_read_b128 v[212:215], v150 offset:19456
	ds_read_b128 v[216:219], v150 offset:20480
	ds_read_b128 v[220:223], v150 offset:21504
	ds_read_b128 v[224:227], v150 offset:22528
	ds_read_b128 v[228:231], v150 offset:23552
	global_load_lds_dwordx4 v132, s[22:23]
	s_mov_b32 m0, s43
	s_addc_u32 s61, s23, 0
	global_load_lds_dwordx4 v136, s[22:23]
	s_mov_b32 m0, s44
	s_nop 0
	global_load_lds_dwordx4 v132, s[60:61]
	s_mov_b32 m0, s45
	s_nop 0
	global_load_lds_dwordx4 v136, s[60:61]
	s_mov_b32 m0, s29
	s_nop 0
	global_load_lds_dwordx4 v130, s[24:25]
	s_mov_b32 m0, s30
	s_nop 0
	global_load_lds_dwordx4 v134, s[24:25]
	s_waitcnt vmcnt(8)
	s_waitcnt lgkmcnt(0)
	s_barrier
	s_setprio 1
	s_waitcnt lgkmcnt(0)
	v_mfma_f32_16x16x32_bf16 v[62:65], v[142:145], v[192:195], v[62:65]
	v_mfma_f32_16x16x32_bf16 v[58:61], v[158:161], v[192:195], v[58:61]
	v_mfma_f32_16x16x32_bf16 v[46:49], v[142:145], v[208:211], v[46:49]
	v_mfma_f32_16x16x32_bf16 v[42:45], v[158:161], v[208:211], v[42:45]
	v_mfma_f32_16x16x32_bf16 v[30:33], v[142:145], v[216:219], v[30:33]
	v_mfma_f32_16x16x32_bf16 v[26:29], v[158:161], v[216:219], v[26:29]
	v_mfma_f32_16x16x32_bf16 v[14:17], v[142:145], v[224:227], v[14:17]
	v_mfma_f32_16x16x32_bf16 v[10:13], v[158:161], v[224:227], v[10:13]
	v_mfma_f32_16x16x32_bf16 v[62:65], v[154:157], v[204:207], v[62:65]
	v_mfma_f32_16x16x32_bf16 v[58:61], v[168:171], v[204:207], v[58:61]
	v_mfma_f32_16x16x32_bf16 v[46:49], v[154:157], v[212:215], v[46:49]
	v_mfma_f32_16x16x32_bf16 v[42:45], v[168:171], v[212:215], v[42:45]
	v_mfma_f32_16x16x32_bf16 v[30:33], v[154:157], v[220:223], v[30:33]
	v_mfma_f32_16x16x32_bf16 v[26:29], v[168:171], v[220:223], v[26:29]
	v_mfma_f32_16x16x32_bf16 v[14:17], v[154:157], v[228:231], v[14:17]
	v_mfma_f32_16x16x32_bf16 v[10:13], v[168:171], v[228:231], v[10:13]
	s_setprio 0
	s_setprio 1
	v_mfma_f32_16x16x32_bf16 v[54:57], v[176:179], v[192:195], v[54:57]
	v_mfma_f32_16x16x32_bf16 v[50:53], v[184:187], v[192:195], v[50:53]
	v_mfma_f32_16x16x32_bf16 v[38:41], v[176:179], v[208:211], v[38:41]
	v_mfma_f32_16x16x32_bf16 v[34:37], v[184:187], v[208:211], v[34:37]
	v_mfma_f32_16x16x32_bf16 v[22:25], v[176:179], v[216:219], v[22:25]
	v_mfma_f32_16x16x32_bf16 v[18:21], v[184:187], v[216:219], v[18:21]
	v_mfma_f32_16x16x32_bf16 v[6:9], v[176:179], v[224:227], v[6:9]
	v_mfma_f32_16x16x32_bf16 v[2:5], v[184:187], v[224:227], v[2:5]
	v_mfma_f32_16x16x32_bf16 v[54:57], v[180:183], v[204:207], v[54:57]
	v_mfma_f32_16x16x32_bf16 v[50:53], v[188:191], v[204:207], v[50:53]
	v_mfma_f32_16x16x32_bf16 v[38:41], v[180:183], v[212:215], v[38:41]
	v_mfma_f32_16x16x32_bf16 v[34:37], v[188:191], v[212:215], v[34:37]
	v_mfma_f32_16x16x32_bf16 v[22:25], v[180:183], v[220:223], v[22:25]
	v_mfma_f32_16x16x32_bf16 v[18:21], v[188:191], v[220:223], v[18:21]
	v_mfma_f32_16x16x32_bf16 v[6:9], v[180:183], v[228:231], v[6:9]
	v_mfma_f32_16x16x32_bf16 v[2:5], v[188:191], v[228:231], v[2:5]
	s_setprio 0
	s_barrier
	ds_read_b128 v[142:145], v151
	ds_read_b128 v[154:157], v151 offset:1024
	ds_read_b128 v[158:161], v151 offset:2048
	ds_read_b128 v[168:171], v151 offset:3072
	ds_read_b128 v[176:179], v152
	ds_read_b128 v[180:183], v152 offset:1024
	ds_read_b128 v[184:187], v152 offset:2048
	ds_read_b128 v[188:191], v152 offset:3072
	s_add_u32 s24, s24, 0x100000
	s_addc_u32 s25, s25, 0
	s_mov_b32 m0, s31
	ds_read_b128 v[192:195], v150 offset:32768
	ds_read_b128 v[204:207], v150 offset:33792
	ds_read_b128 v[208:211], v150 offset:34816
	ds_read_b128 v[212:215], v150 offset:35840
	ds_read_b128 v[216:219], v150 offset:36864
	ds_read_b128 v[220:223], v150 offset:37888
	ds_read_b128 v[224:227], v150 offset:38912
	ds_read_b128 v[228:231], v150 offset:39936
	global_load_lds_dwordx4 v130, s[24:25]
	s_mov_b32 m0, s33
	s_nop 0
	global_load_lds_dwordx4 v134, s[24:25]
	s_waitcnt vmcnt(8)
	s_waitcnt lgkmcnt(0)
	s_barrier
	s_setprio 1
	s_waitcnt lgkmcnt(0)
	v_mfma_f32_16x16x32_bf16 v[126:129], v[142:145], v[192:195], v[126:129]
	v_mfma_f32_16x16x32_bf16 v[122:125], v[158:161], v[192:195], v[122:125]
	v_mfma_f32_16x16x32_bf16 v[110:113], v[142:145], v[208:211], v[110:113]
	v_mfma_f32_16x16x32_bf16 v[106:109], v[158:161], v[208:211], v[106:109]
	v_mfma_f32_16x16x32_bf16 v[94:97], v[142:145], v[216:219], v[94:97]
	v_mfma_f32_16x16x32_bf16 v[90:93], v[158:161], v[216:219], v[90:93]
	v_mfma_f32_16x16x32_bf16 v[78:81], v[142:145], v[224:227], v[78:81]
	v_mfma_f32_16x16x32_bf16 v[74:77], v[158:161], v[224:227], v[74:77]
	v_mfma_f32_16x16x32_bf16 v[126:129], v[154:157], v[204:207], v[126:129]
	v_mfma_f32_16x16x32_bf16 v[122:125], v[168:171], v[204:207], v[122:125]
	v_mfma_f32_16x16x32_bf16 v[110:113], v[154:157], v[212:215], v[110:113]
	v_mfma_f32_16x16x32_bf16 v[106:109], v[168:171], v[212:215], v[106:109]
	v_mfma_f32_16x16x32_bf16 v[94:97], v[154:157], v[220:223], v[94:97]
	v_mfma_f32_16x16x32_bf16 v[90:93], v[168:171], v[220:223], v[90:93]
	v_mfma_f32_16x16x32_bf16 v[78:81], v[154:157], v[228:231], v[78:81]
	v_mfma_f32_16x16x32_bf16 v[74:77], v[168:171], v[228:231], v[74:77]
	s_setprio 0
	s_setprio 1
	v_mfma_f32_16x16x32_bf16 v[118:121], v[176:179], v[192:195], v[118:121]
	v_mfma_f32_16x16x32_bf16 v[114:117], v[184:187], v[192:195], v[114:117]
	v_mfma_f32_16x16x32_bf16 v[102:105], v[176:179], v[208:211], v[102:105]
	v_mfma_f32_16x16x32_bf16 v[98:101], v[184:187], v[208:211], v[98:101]
	v_mfma_f32_16x16x32_bf16 v[86:89], v[176:179], v[216:219], v[86:89]
	v_mfma_f32_16x16x32_bf16 v[82:85], v[184:187], v[216:219], v[82:85]
	v_mfma_f32_16x16x32_bf16 v[70:73], v[176:179], v[224:227], v[70:73]
	v_mfma_f32_16x16x32_bf16 v[66:69], v[184:187], v[224:227], v[66:69]
	v_mfma_f32_16x16x32_bf16 v[118:121], v[180:183], v[204:207], v[118:121]
	v_mfma_f32_16x16x32_bf16 v[114:117], v[188:191], v[204:207], v[114:117]
	v_mfma_f32_16x16x32_bf16 v[102:105], v[180:183], v[212:215], v[102:105]
	v_mfma_f32_16x16x32_bf16 v[98:101], v[188:191], v[212:215], v[98:101]
	v_mfma_f32_16x16x32_bf16 v[86:89], v[180:183], v[220:223], v[86:89]
	v_mfma_f32_16x16x32_bf16 v[82:85], v[188:191], v[220:223], v[82:85]
	v_mfma_f32_16x16x32_bf16 v[70:73], v[180:183], v[228:231], v[70:73]
	v_mfma_f32_16x16x32_bf16 v[66:69], v[188:191], v[228:231], v[66:69]
	s_setprio 0
	s_barrier
	s_mov_b32 m0, s46
	s_add_u32 s22, s22, 0x80
	s_addc_u32 s23, s23, 0
	ds_read_b128 v[192:195], v150 offset:49152
	ds_read_b128 v[204:207], v150 offset:50176
	ds_read_b128 v[208:211], v150 offset:51200
	ds_read_b128 v[212:215], v150 offset:52224
	ds_read_b128 v[216:219], v150 offset:53248
	ds_read_b128 v[220:223], v150 offset:54272
	ds_read_b128 v[224:227], v150 offset:55296
	ds_read_b128 v[228:231], v150 offset:56320
	global_load_lds_dwordx4 v132, s[22:23]
	s_mov_b32 m0, s47
	s_add_u32 s60, s24, 0xfff00080
	s_addc_u32 s61, s25, -1
	global_load_lds_dwordx4 v136, s[22:23]
	s_mov_b32 m0, s48
	s_add_u32 s22, s22, 0x100000
	s_addc_u32 s23, s23, 0
	global_load_lds_dwordx4 v132, s[22:23]
	s_mov_b32 m0, s49
	s_nop 0
	global_load_lds_dwordx4 v136, s[22:23]
	s_mov_b32 m0, s35
	s_nop 0
	global_load_lds_dwordx4 v130, s[60:61]
	s_mov_b32 m0, s36
	s_nop 0
	global_load_lds_dwordx4 v134, s[60:61]
	s_waitcnt vmcnt(8)
	s_waitcnt lgkmcnt(0)
	s_barrier
	s_setprio 1
	s_waitcnt lgkmcnt(0)
	v_mfma_f32_16x16x32_bf16 v[62:65], v[142:145], v[192:195], v[62:65]
	v_mfma_f32_16x16x32_bf16 v[58:61], v[158:161], v[192:195], v[58:61]
	v_mfma_f32_16x16x32_bf16 v[46:49], v[142:145], v[208:211], v[46:49]
	v_mfma_f32_16x16x32_bf16 v[42:45], v[158:161], v[208:211], v[42:45]
	v_mfma_f32_16x16x32_bf16 v[30:33], v[142:145], v[216:219], v[30:33]
	v_mfma_f32_16x16x32_bf16 v[26:29], v[158:161], v[216:219], v[26:29]
	v_mfma_f32_16x16x32_bf16 v[14:17], v[142:145], v[224:227], v[14:17]
	v_mfma_f32_16x16x32_bf16 v[10:13], v[158:161], v[224:227], v[10:13]
	v_mfma_f32_16x16x32_bf16 v[62:65], v[154:157], v[204:207], v[62:65]
	v_mfma_f32_16x16x32_bf16 v[58:61], v[168:171], v[204:207], v[58:61]
	v_mfma_f32_16x16x32_bf16 v[46:49], v[154:157], v[212:215], v[46:49]
	v_mfma_f32_16x16x32_bf16 v[42:45], v[168:171], v[212:215], v[42:45]
	v_mfma_f32_16x16x32_bf16 v[30:33], v[154:157], v[220:223], v[30:33]
	v_mfma_f32_16x16x32_bf16 v[26:29], v[168:171], v[220:223], v[26:29]
	v_mfma_f32_16x16x32_bf16 v[14:17], v[154:157], v[228:231], v[14:17]
	v_mfma_f32_16x16x32_bf16 v[10:13], v[168:171], v[228:231], v[10:13]
	s_setprio 0
	s_setprio 1
	v_mfma_f32_16x16x32_bf16 v[54:57], v[176:179], v[192:195], v[54:57]
	v_mfma_f32_16x16x32_bf16 v[50:53], v[184:187], v[192:195], v[50:53]
	v_mfma_f32_16x16x32_bf16 v[38:41], v[176:179], v[208:211], v[38:41]
	v_mfma_f32_16x16x32_bf16 v[34:37], v[184:187], v[208:211], v[34:37]
	v_mfma_f32_16x16x32_bf16 v[22:25], v[176:179], v[216:219], v[22:25]
	v_mfma_f32_16x16x32_bf16 v[18:21], v[184:187], v[216:219], v[18:21]
	v_mfma_f32_16x16x32_bf16 v[6:9], v[176:179], v[224:227], v[6:9]
	v_mfma_f32_16x16x32_bf16 v[2:5], v[184:187], v[224:227], v[2:5]
	v_mfma_f32_16x16x32_bf16 v[54:57], v[180:183], v[204:207], v[54:57]
	v_mfma_f32_16x16x32_bf16 v[50:53], v[188:191], v[204:207], v[50:53]
	v_mfma_f32_16x16x32_bf16 v[38:41], v[180:183], v[212:215], v[38:41]
	v_mfma_f32_16x16x32_bf16 v[34:37], v[188:191], v[212:215], v[34:37]
	v_mfma_f32_16x16x32_bf16 v[22:25], v[180:183], v[220:223], v[22:25]
	v_mfma_f32_16x16x32_bf16 v[18:21], v[188:191], v[220:223], v[18:21]
	v_mfma_f32_16x16x32_bf16 v[6:9], v[180:183], v[228:231], v[6:9]
	v_mfma_f32_16x16x32_bf16 v[2:5], v[188:191], v[228:231], v[2:5]
	s_setprio 0
	s_barrier
	s_add_i32 s57, s57, 2
	s_add_u32 s20, s20, 0x100
	s_addc_u32 s21, s21, 0
	s_add_u32 s55, s55, 0x100
	s_addc_u32 s56, s56, 0
	s_cmp_gt_u32 s57, 61
	s_cbranch_scc0 .LBB0_2373
	s_and_b64 vcc, exec, s[16:17]
	s_cbranch_vccz .LBB0_2376
	s_barrier

.LBB0_2618:
	ds_read_b128 v[142:145], v156
	ds_read_b128 v[168:171], v156 offset:1024
	ds_read_b128 v[172:175], v156 offset:2048
	ds_read_b128 v[176:179], v156 offset:3072
	ds_read_b128 v[180:183], v157
	ds_read_b128 v[184:187], v157 offset:1024
	ds_read_b128 v[188:191], v157 offset:2048
	ds_read_b128 v[192:195], v157 offset:3072
	s_add_u32 s30, s28, 0xffd50080
	s_addc_u32 s31, s29, -1
	s_cmpk_eq_i32 s62, 0xa8
	s_cselect_b32 s35, s25, s31
	s_cselect_b32 s34, s24, s30
	s_cselect_b32 s31, s23, s61
	s_cselect_b32 s30, s22, s60
	s_mov_b32 m0, s46
	ds_read_b128 v[196:199], v158
	ds_read_b128 v[200:203], v158 offset:1024
	ds_read_b128 v[204:207], v158 offset:2048
	ds_read_b128 v[208:211], v158 offset:3072
	ds_read_b128 v[212:215], v158 offset:4096
	ds_read_b128 v[216:219], v158 offset:5120
	ds_read_b128 v[220:223], v158 offset:6144
	ds_read_b128 v[224:227], v158 offset:7168
	global_load_lds_dwordx4 v138, s[28:29]
	s_mov_b32 m0, s47
	s_nop 0
	global_load_lds_dwordx4 v140, s[28:29]
	s_waitcnt vmcnt(8)
	s_waitcnt lgkmcnt(0)
	s_barrier
	s_setprio 1
	s_waitcnt lgkmcnt(0)
	v_mfma_f32_16x16x32_bf16 v[126:129], v[142:145], v[196:199], v[126:129]
	v_mfma_f32_16x16x32_bf16 v[122:125], v[172:175], v[196:199], v[122:125]
	v_mfma_f32_16x16x32_bf16 v[110:113], v[142:145], v[204:207], v[110:113]
	v_mfma_f32_16x16x32_bf16 v[106:109], v[172:175], v[204:207], v[106:109]
	v_mfma_f32_16x16x32_bf16 v[94:97], v[142:145], v[212:215], v[94:97]
	v_mfma_f32_16x16x32_bf16 v[90:93], v[172:175], v[212:215], v[90:93]
	v_mfma_f32_16x16x32_bf16 v[78:81], v[142:145], v[220:223], v[78:81]
	v_mfma_f32_16x16x32_bf16 v[74:77], v[172:175], v[220:223], v[74:77]
	v_mfma_f32_16x16x32_bf16 v[126:129], v[168:171], v[200:203], v[126:129]
	v_mfma_f32_16x16x32_bf16 v[122:125], v[176:179], v[200:203], v[122:125]
	v_mfma_f32_16x16x32_bf16 v[110:113], v[168:171], v[208:211], v[110:113]
	v_mfma_f32_16x16x32_bf16 v[106:109], v[176:179], v[208:211], v[106:109]
	v_mfma_f32_16x16x32_bf16 v[94:97], v[168:171], v[216:219], v[94:97]
	v_mfma_f32_16x16x32_bf16 v[90:93], v[176:179], v[216:219], v[90:93]
	v_mfma_f32_16x16x32_bf16 v[78:81], v[168:171], v[224:227], v[78:81]
	v_mfma_f32_16x16x32_bf16 v[74:77], v[176:179], v[224:227], v[74:77]
	s_setprio 0
	s_setprio 1
	v_mfma_f32_16x16x32_bf16 v[118:121], v[180:183], v[196:199], v[118:121]
	v_mfma_f32_16x16x32_bf16 v[114:117], v[188:191], v[196:199], v[114:117]
	v_mfma_f32_16x16x32_bf16 v[102:105], v[180:183], v[204:207], v[102:105]
	v_mfma_f32_16x16x32_bf16 v[98:101], v[188:191], v[204:207], v[98:101]
	v_mfma_f32_16x16x32_bf16 v[86:89], v[180:183], v[212:215], v[86:89]
	v_mfma_f32_16x16x32_bf16 v[82:85], v[188:191], v[212:215], v[82:85]
	v_mfma_f32_16x16x32_bf16 v[70:73], v[180:183], v[220:223], v[70:73]
	v_mfma_f32_16x16x32_bf16 v[66:69], v[188:191], v[220:223], v[66:69]
	v_mfma_f32_16x16x32_bf16 v[118:121], v[184:187], v[200:203], v[118:121]
	v_mfma_f32_16x16x32_bf16 v[114:117], v[192:195], v[200:203], v[114:117]
	v_mfma_f32_16x16x32_bf16 v[102:105], v[184:187], v[208:211], v[102:105]
	v_mfma_f32_16x16x32_bf16 v[98:101], v[192:195], v[208:211], v[98:101]
	v_mfma_f32_16x16x32_bf16 v[86:89], v[184:187], v[216:219], v[86:89]
	v_mfma_f32_16x16x32_bf16 v[82:85], v[192:195], v[216:219], v[82:85]
	v_mfma_f32_16x16x32_bf16 v[70:73], v[184:187], v[224:227], v[70:73]
	v_mfma_f32_16x16x32_bf16 v[66:69], v[192:195], v[224:227], v[66:69]
	s_setprio 0
	s_barrier
	s_mov_b32 m0, s48
	s_add_u32 s64, s30, 0x2b0000
	ds_read_b128 v[196:199], v158 offset:16384
	ds_read_b128 v[200:203], v158 offset:17408
	ds_read_b128 v[204:207], v158 offset:18432
	ds_read_b128 v[208:211], v158 offset:19456
	ds_read_b128 v[212:215], v158 offset:20480
	ds_read_b128 v[216:219], v158 offset:21504
	ds_read_b128 v[220:223], v158 offset:22528
	ds_read_b128 v[224:227], v158 offset:23552
	global_load_lds_dwordx4 v132, s[30:31]
	s_mov_b32 m0, s49
	s_addc_u32 s65, s31, 0
	global_load_lds_dwordx4 v136, s[30:31]
	s_mov_b32 m0, s50
	s_nop 0
	global_load_lds_dwordx4 v132, s[64:65]
	s_mov_b32 m0, s51
	s_nop 0
	global_load_lds_dwordx4 v136, s[64:65]
	s_mov_b32 m0, s39
	s_nop 0
	global_load_lds_dwordx4 v130, s[34:35]
	s_mov_b32 m0, s40
	s_nop 0
	global_load_lds_dwordx4 v134, s[34:35]
	s_waitcnt vmcnt(8)
	s_waitcnt lgkmcnt(0)
	s_barrier
	s_setprio 1
	s_waitcnt lgkmcnt(0)
	v_mfma_f32_16x16x32_bf16 v[62:65], v[142:145], v[196:199], v[62:65]
	v_mfma_f32_16x16x32_bf16 v[58:61], v[172:175], v[196:199], v[58:61]
	v_mfma_f32_16x16x32_bf16 v[46:49], v[142:145], v[204:207], v[46:49]
	v_mfma_f32_16x16x32_bf16 v[42:45], v[172:175], v[204:207], v[42:45]
	v_mfma_f32_16x16x32_bf16 v[30:33], v[142:145], v[212:215], v[30:33]
	v_mfma_f32_16x16x32_bf16 v[26:29], v[172:175], v[212:215], v[26:29]
	v_mfma_f32_16x16x32_bf16 v[14:17], v[142:145], v[220:223], v[14:17]
	v_mfma_f32_16x16x32_bf16 v[10:13], v[172:175], v[220:223], v[10:13]
	v_mfma_f32_16x16x32_bf16 v[62:65], v[168:171], v[200:203], v[62:65]
	v_mfma_f32_16x16x32_bf16 v[58:61], v[176:179], v[200:203], v[58:61]
	v_mfma_f32_16x16x32_bf16 v[46:49], v[168:171], v[208:211], v[46:49]
	v_mfma_f32_16x16x32_bf16 v[42:45], v[176:179], v[208:211], v[42:45]
	v_mfma_f32_16x16x32_bf16 v[30:33], v[168:171], v[216:219], v[30:33]
	v_mfma_f32_16x16x32_bf16 v[26:29], v[176:179], v[216:219], v[26:29]
	v_mfma_f32_16x16x32_bf16 v[14:17], v[168:171], v[224:227], v[14:17]
	v_mfma_f32_16x16x32_bf16 v[10:13], v[176:179], v[224:227], v[10:13]
	s_setprio 0
	s_setprio 1
	v_mfma_f32_16x16x32_bf16 v[54:57], v[180:183], v[196:199], v[54:57]
	v_mfma_f32_16x16x32_bf16 v[50:53], v[188:191], v[196:199], v[50:53]
	v_mfma_f32_16x16x32_bf16 v[38:41], v[180:183], v[204:207], v[38:41]
	v_mfma_f32_16x16x32_bf16 v[34:37], v[188:191], v[204:207], v[34:37]
	v_mfma_f32_16x16x32_bf16 v[22:25], v[180:183], v[212:215], v[22:25]
	v_mfma_f32_16x16x32_bf16 v[18:21], v[188:191], v[212:215], v[18:21]
	v_mfma_f32_16x16x32_bf16 v[6:9], v[180:183], v[220:223], v[6:9]
	v_mfma_f32_16x16x32_bf16 v[2:5], v[188:191], v[220:223], v[2:5]
	v_mfma_f32_16x16x32_bf16 v[54:57], v[184:187], v[200:203], v[54:57]
	v_mfma_f32_16x16x32_bf16 v[50:53], v[192:195], v[200:203], v[50:53]
	v_mfma_f32_16x16x32_bf16 v[38:41], v[184:187], v[208:211], v[38:41]
	v_mfma_f32_16x16x32_bf16 v[34:37], v[192:195], v[208:211], v[34:37]
	v_mfma_f32_16x16x32_bf16 v[22:25], v[184:187], v[216:219], v[22:25]
	v_mfma_f32_16x16x32_bf16 v[18:21], v[192:195], v[216:219], v[18:21]
	v_mfma_f32_16x16x32_bf16 v[6:9], v[184:187], v[224:227], v[6:9]
	v_mfma_f32_16x16x32_bf16 v[2:5], v[192:195], v[224:227], v[2:5]
	s_setprio 0
	s_barrier
	ds_read_b128 v[142:145], v159
	ds_read_b128 v[168:171], v159 offset:1024
	ds_read_b128 v[172:175], v159 offset:2048
	ds_read_b128 v[176:179], v159 offset:3072
	ds_read_b128 v[180:183], v160
	ds_read_b128 v[184:187], v160 offset:1024
	ds_read_b128 v[188:191], v160 offset:2048
	ds_read_b128 v[192:195], v160 offset:3072
	s_add_u32 s34, s34, 0x2b0000
	s_addc_u32 s35, s35, 0
	s_mov_b32 m0, s41
	ds_read_b128 v[196:199], v158 offset:32768
	ds_read_b128 v[200:203], v158 offset:33792
	ds_read_b128 v[204:207], v158 offset:34816
	ds_read_b128 v[208:211], v158 offset:35840
	ds_read_b128 v[212:215], v158 offset:36864
	ds_read_b128 v[216:219], v158 offset:37888
	ds_read_b128 v[220:223], v158 offset:38912
	ds_read_b128 v[224:227], v158 offset:39936
	global_load_lds_dwordx4 v130, s[34:35]
	s_mov_b32 m0, s42
	s_nop 0
	global_load_lds_dwordx4 v134, s[34:35]
	s_waitcnt vmcnt(8)
	s_waitcnt lgkmcnt(0)
	s_barrier
	s_setprio 1
	s_waitcnt lgkmcnt(0)
	v_mfma_f32_16x16x32_bf16 v[126:129], v[142:145], v[196:199], v[126:129]
	v_mfma_f32_16x16x32_bf16 v[122:125], v[172:175], v[196:199], v[122:125]
	v_mfma_f32_16x16x32_bf16 v[110:113], v[142:145], v[204:207], v[110:113]
	v_mfma_f32_16x16x32_bf16 v[106:109], v[172:175], v[204:207], v[106:109]
	v_mfma_f32_16x16x32_bf16 v[94:97], v[142:145], v[212:215], v[94:97]
	v_mfma_f32_16x16x32_bf16 v[90:93], v[172:175], v[212:215], v[90:93]
	v_mfma_f32_16x16x32_bf16 v[78:81], v[142:145], v[220:223], v[78:81]
	v_mfma_f32_16x16x32_bf16 v[74:77], v[172:175], v[220:223], v[74:77]
	v_mfma_f32_16x16x32_bf16 v[126:129], v[168:171], v[200:203], v[126:129]
	v_mfma_f32_16x16x32_bf16 v[122:125], v[176:179], v[200:203], v[122:125]
	v_mfma_f32_16x16x32_bf16 v[110:113], v[168:171], v[208:211], v[110:113]
	v_mfma_f32_16x16x32_bf16 v[106:109], v[176:179], v[208:211], v[106:109]
	v_mfma_f32_16x16x32_bf16 v[94:97], v[168:171], v[216:219], v[94:97]
	v_mfma_f32_16x16x32_bf16 v[90:93], v[176:179], v[216:219], v[90:93]
	v_mfma_f32_16x16x32_bf16 v[78:81], v[168:171], v[224:227], v[78:81]
	v_mfma_f32_16x16x32_bf16 v[74:77], v[176:179], v[224:227], v[74:77]
	s_setprio 0
	s_setprio 1
	v_mfma_f32_16x16x32_bf16 v[118:121], v[180:183], v[196:199], v[118:121]
	v_mfma_f32_16x16x32_bf16 v[114:117], v[188:191], v[196:199], v[114:117]
	v_mfma_f32_16x16x32_bf16 v[102:105], v[180:183], v[204:207], v[102:105]
	v_mfma_f32_16x16x32_bf16 v[98:101], v[188:191], v[204:207], v[98:101]
	v_mfma_f32_16x16x32_bf16 v[86:89], v[180:183], v[212:215], v[86:89]
	v_mfma_f32_16x16x32_bf16 v[82:85], v[188:191], v[212:215], v[82:85]
	v_mfma_f32_16x16x32_bf16 v[70:73], v[180:183], v[220:223], v[70:73]
	v_mfma_f32_16x16x32_bf16 v[66:69], v[188:191], v[220:223], v[66:69]
	v_mfma_f32_16x16x32_bf16 v[118:121], v[184:187], v[200:203], v[118:121]
	v_mfma_f32_16x16x32_bf16 v[114:117], v[192:195], v[200:203], v[114:117]
	v_mfma_f32_16x16x32_bf16 v[102:105], v[184:187], v[208:211], v[102:105]
	v_mfma_f32_16x16x32_bf16 v[98:101], v[192:195], v[208:211], v[98:101]
	v_mfma_f32_16x16x32_bf16 v[86:89], v[184:187], v[216:219], v[86:89]
	v_mfma_f32_16x16x32_bf16 v[82:85], v[192:195], v[216:219], v[82:85]
	v_mfma_f32_16x16x32_bf16 v[70:73], v[184:187], v[224:227], v[70:73]
	v_mfma_f32_16x16x32_bf16 v[66:69], v[192:195], v[224:227], v[66:69]
	s_setprio 0
	s_barrier
	s_mov_b32 m0, s52
	s_add_u32 s30, s30, 0x80
	s_addc_u32 s31, s31, 0
	ds_read_b128 v[196:199], v158 offset:49152
	ds_read_b128 v[200:203], v158 offset:50176
	ds_read_b128 v[204:207], v158 offset:51200
	ds_read_b128 v[208:211], v158 offset:52224
	ds_read_b128 v[212:215], v158 offset:53248
	ds_read_b128 v[216:219], v158 offset:54272
	ds_read_b128 v[220:223], v158 offset:55296
	ds_read_b128 v[224:227], v158 offset:56320
	global_load_lds_dwordx4 v132, s[30:31]
	s_mov_b32 m0, s53
	s_add_u32 s64, s34, 0xffd50080
	s_addc_u32 s65, s35, -1
	global_load_lds_dwordx4 v136, s[30:31]
	s_mov_b32 m0, s54
	s_add_u32 s30, s30, 0x2b0000
	s_addc_u32 s31, s31, 0
	global_load_lds_dwordx4 v132, s[30:31]
	s_mov_b32 m0, s55
	s_nop 0
	global_load_lds_dwordx4 v136, s[30:31]
	s_mov_b32 m0, s44
	s_nop 0
	global_load_lds_dwordx4 v130, s[64:65]
	s_mov_b32 m0, s45
	s_nop 0
	global_load_lds_dwordx4 v134, s[64:65]
	s_waitcnt vmcnt(8)
	s_waitcnt lgkmcnt(0)
	s_barrier
	s_setprio 1
	s_waitcnt lgkmcnt(0)
	v_mfma_f32_16x16x32_bf16 v[62:65], v[142:145], v[196:199], v[62:65]
	v_mfma_f32_16x16x32_bf16 v[58:61], v[172:175], v[196:199], v[58:61]
	v_mfma_f32_16x16x32_bf16 v[46:49], v[142:145], v[204:207], v[46:49]
	v_mfma_f32_16x16x32_bf16 v[42:45], v[172:175], v[204:207], v[42:45]
	v_mfma_f32_16x16x32_bf16 v[30:33], v[142:145], v[212:215], v[30:33]
	v_mfma_f32_16x16x32_bf16 v[26:29], v[172:175], v[212:215], v[26:29]
	v_mfma_f32_16x16x32_bf16 v[14:17], v[142:145], v[220:223], v[14:17]
	v_mfma_f32_16x16x32_bf16 v[10:13], v[172:175], v[220:223], v[10:13]
	v_mfma_f32_16x16x32_bf16 v[62:65], v[168:171], v[200:203], v[62:65]
	v_mfma_f32_16x16x32_bf16 v[58:61], v[176:179], v[200:203], v[58:61]
	v_mfma_f32_16x16x32_bf16 v[46:49], v[168:171], v[208:211], v[46:49]
	v_mfma_f32_16x16x32_bf16 v[42:45], v[176:179], v[208:211], v[42:45]
	v_mfma_f32_16x16x32_bf16 v[30:33], v[168:171], v[216:219], v[30:33]
	v_mfma_f32_16x16x32_bf16 v[26:29], v[176:179], v[216:219], v[26:29]
	v_mfma_f32_16x16x32_bf16 v[14:17], v[168:171], v[224:227], v[14:17]
	v_mfma_f32_16x16x32_bf16 v[10:13], v[176:179], v[224:227], v[10:13]
	s_setprio 0
	s_setprio 1
	v_mfma_f32_16x16x32_bf16 v[54:57], v[180:183], v[196:199], v[54:57]
	v_mfma_f32_16x16x32_bf16 v[50:53], v[188:191], v[196:199], v[50:53]
	v_mfma_f32_16x16x32_bf16 v[38:41], v[180:183], v[204:207], v[38:41]
	v_mfma_f32_16x16x32_bf16 v[34:37], v[188:191], v[204:207], v[34:37]
	v_mfma_f32_16x16x32_bf16 v[22:25], v[180:183], v[212:215], v[22:25]
	v_mfma_f32_16x16x32_bf16 v[18:21], v[188:191], v[212:215], v[18:21]
	v_mfma_f32_16x16x32_bf16 v[6:9], v[180:183], v[220:223], v[6:9]
	v_mfma_f32_16x16x32_bf16 v[2:5], v[188:191], v[220:223], v[2:5]
	v_mfma_f32_16x16x32_bf16 v[54:57], v[184:187], v[200:203], v[54:57]
	v_mfma_f32_16x16x32_bf16 v[50:53], v[192:195], v[200:203], v[50:53]
	v_mfma_f32_16x16x32_bf16 v[38:41], v[184:187], v[208:211], v[38:41]
	v_mfma_f32_16x16x32_bf16 v[34:37], v[192:195], v[208:211], v[34:37]
	v_mfma_f32_16x16x32_bf16 v[22:25], v[184:187], v[216:219], v[22:25]
	v_mfma_f32_16x16x32_bf16 v[18:21], v[192:195], v[216:219], v[18:21]
	v_mfma_f32_16x16x32_bf16 v[6:9], v[184:187], v[224:227], v[6:9]
	v_mfma_f32_16x16x32_bf16 v[2:5], v[192:195], v[224:227], v[2:5]
	s_setprio 0
	s_barrier
	s_add_i32 s62, s62, 2
	s_add_u32 s28, s28, 0x100
	s_addc_u32 s29, s29, 0
	s_add_u32 s60, s60, 0x100
	s_addc_u32 s61, s61, 0
	s_cmpk_gt_u32 s62, 0xa9
	s_cbranch_scc0 .LBB0_2618
	s_and_b64 vcc, exec, s[12:13]
	s_cbranch_vccz .LBB0_2621
	s_barrier
